# attn_a v7: K/V tiles staged in LDS from coalesced row loads, K frags via ds_read_b128, V operands via ds_read_b64_tr_b16
# speedup vs baseline: 1.3334x; 1.0051x over previous
; DI void phase_attn_a(int wv_, int vb_, int nvb_, char* ws_, const Ctx& p, char* smem) {
;     ...
;   const int tid = tidx(wv_), lane = tid & 63, wave = tid >> 6, c = lane & 31, h = lane >> 5;
;   for (int k_ = 0; k_ < (6144 + nvb_ - 1) / nvb_; ++k_) {
;     const int u = (vb_ + k_ * nvb_ < 6144) ? vb_ + k_ * nvb_ : 6143;
;     const int head = u & 7, g = (u >> 3) % 3, rest = u / 24, idx = rest & 31, b = rest >> 5;
;     const int dil = (g == 0) ? 1 : ((g == 1) ? 4 : 16);
;     const int nbper = 32 / dil, r = idx / nbper, nb = idx % nbper;
;     u16* Og = (g == 0) ? (u16*)(ws_ + WS_H) : ((g == 1) ? (u16*)(ws_ + WS_H + 32 * MiB) : (u16*)(ws_ + WS_E));
;     float* lse = (float*)(ws_ + WS_LSE) + (size_t)g * NTOK * 8;
;     if (tid <= 128) sBias[tid] = p.rel_bias[t5_bucket(tid * dil) * 40 + g * 8 + head] * 1.4426950408889634f;
;     {
;       const int kk = tid; const int ksub = nb * 128 - 128 + kk;
;       bf16x8 v[8];
;       if (ksub >= 0) {
;         const u16* vp = P + ((size_t)b * SEQ + (size_t)ksub * dil + r) * 4608 + 3072 + g * 512 + head * 64;
; #pragma unroll
;         for (int i = 0; i < 8; ++i) v[i] = *(const bf16x8*)(vp + i * 8);
;       } else {
; #pragma unroll
;         for (int i = 0; i < 8; ++i) v[i] = zero8();
;       }
; #pragma unroll
;       for (int i = 0; i < 8; ++i)
; #pragma unroll
;         for (int jj = 0; jj < 8; ++jj) Vt[(i * 8 + jj) * 260 + kk] = (u16)v[i][jj];
;     }
;     __syncthreads();
.LBB0_493:
	v_writelane_b32 v255, s54, 5
	s_cmp_lt_i32 s23, 2
	s_mov_b64 s[2:3], -1
	v_writelane_b32 v255, s55, 6
	s_cbranch_scc1 .LBB0_764
	s_cmp_gt_i32 s23, 2
	s_cbranch_scc0 .LBB0_552
	v_readlane_b32 s2, v253, 27
	v_readlane_b32 s3, v253, 28
	s_mov_b32 s0, s33
	v_mov_b32_e32 v0, v204
	s_andn2_b64 vcc, exec, s[2:3]
	s_cbranch_vccnz .LBB0_551
	s_mov_b32 s60, s33
	v_readlane_b32 s35, v253, 26
	v_readlane_b32 s44, v254, 14
	v_readlane_b32 s45, v254, 56
	v_readlane_b32 s56, v254, 32
	v_readlane_b32 s57, v254, 33
	v_and_b32_e32 v196, 31, v204
	v_lshrrev_b32_e32 v197, 5, v204
	v_lshl_add_u32 v202, s60, 6, v204
	s_lshl_b32 s0, s60, 5
	v_add_u32_e32 v200, s0, v196
	v_lshlrev_b32_e32 v201, 4, v197
	v_lshlrev_b32_e32 v239, 3, v197
	v_lshrrev_b32_e32 v198, 3, v204
	v_lshl_add_u32 v199, s60, 6, v198
	v_add_u32_e32 v240, 0xffffff80, v199
	v_and_b32_e32 v246, 7, v204
	v_lshlrev_b32_e32 v241, 4, v246
	v_lshrrev_b32_e32 v247, 4, v204
	v_xor_b32_e32 v198, v246, v247
	v_lshlrev_b32_e32 v198, 4, v198
	v_lshl_add_u32 v203, v199, 7, v214
	v_add_u32_e32 v203, v203, v198
	v_xor_b32_e32 v198, 64, v198
	v_lshl_add_u32 v209, v199, 7, v214
	v_add_u32_e32 v209, v209, v198
	v_and_b32_e32 v247, 1, v247
	v_lshlrev_b32_e32 v247, 2, v247
	v_xor_b32_e32 v198, v246, v247
	v_lshlrev_b32_e32 v198, 4, v198
	v_lshl_add_u32 v216, v199, 7, v214
	v_add_u32_e32 v216, v216, v198
	v_add_u32_e32 v216, 0x8000, v216
	v_lshl_add_u32 v198, v200, 7, v214
	v_bfe_u32 v199, v196, 1, 3
	v_or_b32_e32 v246, 0, v197
	v_xor_b32_e32 v246, v246, v199
	v_lshl_add_u32 v217, v246, 4, v198
	v_or_b32_e32 v246, 2, v197
	v_xor_b32_e32 v246, v246, v199
	v_lshl_add_u32 v218, v246, 4, v198
	v_or_b32_e32 v246, 4, v197
	v_xor_b32_e32 v246, v246, v199
	v_lshl_add_u32 v219, v246, 4, v198
	v_or_b32_e32 v246, 6, v197
	v_xor_b32_e32 v246, v246, v199
	v_lshl_add_u32 v220, v246, 4, v198
	v_bfe_u32 v198, v196, 2, 2
	v_and_b32_e32 v199, 3, v196
	v_lshrrev_b32_e32 v246, 4, v196
	v_lshl_add_u32 v247, v197, 2, v198
	s_lshl_b32 s1, s60, 5
	v_add_u32_e32 v247, s1, v247
	v_lshl_add_u32 v247, v247, 7, v214
	v_add_u32_e32 v247, 0x8000, v247
	v_lshrrev_b32_e32 v198, 1, v198
	v_lshlrev_b32_e32 v246, 1, v246
	v_lshrrev_b32_e32 v236, 1, v199
	v_add_u32_e32 v246, v246, v236
	v_and_b32_e32 v199, 1, v199
	v_lshl_add_u32 v247, v199, 3, v247
	v_xor_b32_e32 v236, 0, v198
	v_lshl_add_u32 v236, v236, 2, v246
	v_lshl_add_u32 v221, v236, 4, v247
	v_xor_b32_e32 v236, 1, v198
	v_lshl_add_u32 v236, v236, 2, v246
	v_lshl_add_u32 v222, v236, 4, v247
	v_lshl_add_u32 v198, v196, 2, v214
	v_sub_u32_e32 v198, v198, v201
	v_add_u32_e32 v223, 0x10000, v198
	v_lshl_add_u32 v198, v202, 2, v214
	v_add_u32_e32 v224, 0x10000, v198
	v_add_u32_e32 v198, 0xffffffe1, v202
	v_cmp_gt_u32_e32 vcc, 0x81, v198
	s_mov_b64 s[66:67], vcc
	v_max_i32_e32 v198, 0, v198
	v_min_u32_e32 v198, 0x80, v198
	v_lshlrev_b32_e32 v199, 0, v198
	v_mov_b32_e32 v246, 16
	v_cmp_le_u32_e32 vcc, 22, v199
	s_nop 1
	v_addc_co_u32_e32 v246, vcc, 0, v246, vcc
	v_cmp_le_u32_e32 vcc, 30, v199
	s_nop 1
	v_addc_co_u32_e32 v246, vcc, 0, v246, vcc
	v_cmp_le_u32_e32 vcc, 40, v199
	s_nop 1
	v_addc_co_u32_e32 v246, vcc, 0, v246, vcc
	v_cmp_le_u32_e32 vcc, 54, v199
	s_nop 1
	v_addc_co_u32_e32 v246, vcc, 0, v246, vcc
	v_cmp_le_u32_e32 vcc, 0x49, v199
	s_nop 1
	v_addc_co_u32_e32 v246, vcc, 0, v246, vcc
	v_cmp_le_u32_e32 vcc, 0x63, v199
	s_nop 1
	v_addc_co_u32_e32 v246, vcc, 0, v246, vcc
	v_cmp_le_u32_e32 vcc, 0x86, v199
	s_nop 1
	v_addc_co_u32_e32 v246, vcc, 0, v246, vcc
	v_cmp_le_u32_e32 vcc, 0xb6, v199
	s_nop 1
	v_addc_co_u32_e32 v246, vcc, 0, v246, vcc
	v_cmp_le_u32_e32 vcc, 0xf6, v199
	s_nop 1
	v_addc_co_u32_e32 v246, vcc, 0, v246, vcc
	v_cmp_le_u32_e32 vcc, 0x14c, v199
	s_nop 1
	v_addc_co_u32_e32 v246, vcc, 0, v246, vcc
	v_cmp_le_u32_e32 vcc, 0x1c2, v199
	s_nop 1
	v_addc_co_u32_e32 v246, vcc, 0, v246, vcc
	v_cmp_le_u32_e32 vcc, 0x261, v199
	s_nop 1
; DI int t5_bucket(int dist) {
;   if (dist < 16) return dist;
;   float lp = logf((float)dist / 16.0f) / 4.852030263919617f * 16.0f;
;   int b = 16 + (int)lp;
;   return b < 31 ? b : 31;
; }
; DI void phase_attn_a(int wv_, int vb_, int nvb_, char* ws_, const Ctx& p, char* smem) {
;     ...
;   for (int k_ = 0; k_ < (6144 + nvb_ - 1) / nvb_; ++k_) {
;     const int u = (vb_ + k_ * nvb_ < 6144) ? vb_ + k_ * nvb_ : 6143;
;     const int head = u & 7, g = (u >> 3) % 3, rest = u / 24, idx = rest & 31, b = rest >> 5;
	v_addc_co_u32_e32 v246, vcc, 0, v246, vcc
	v_cmp_le_u32_e32 vcc, 0x339, v199
	s_nop 1
	v_addc_co_u32_e32 v246, vcc, 0, v246, vcc
	v_cmp_le_u32_e32 vcc, 0x45d, v199
	s_nop 1
	v_addc_co_u32_e32 v246, vcc, 0, v246, vcc
	v_cmp_le_u32_e32 vcc, 0x5e9, v199
	s_nop 1
	v_addc_co_u32_e32 v246, vcc, 0, v246, vcc
	v_cmp_gt_u32_e32 vcc, 16, v199
	s_nop 1
	v_cndmask_b32_e32 v246, v246, v199, vcc
	v_mul_u32_u24_e32 v106, 0xa0, v246
	v_lshlrev_b32_e32 v199, 2, v198
	v_mov_b32_e32 v246, 16
	v_cmp_le_u32_e32 vcc, 22, v199
	s_nop 1
	v_addc_co_u32_e32 v246, vcc, 0, v246, vcc
	v_cmp_le_u32_e32 vcc, 30, v199
	s_nop 1
	v_addc_co_u32_e32 v246, vcc, 0, v246, vcc
	v_cmp_le_u32_e32 vcc, 40, v199
	s_nop 1
	v_addc_co_u32_e32 v246, vcc, 0, v246, vcc
	v_cmp_le_u32_e32 vcc, 54, v199
	s_nop 1
	v_addc_co_u32_e32 v246, vcc, 0, v246, vcc
	v_cmp_le_u32_e32 vcc, 0x49, v199
	s_nop 1
	v_addc_co_u32_e32 v246, vcc, 0, v246, vcc
	v_cmp_le_u32_e32 vcc, 0x63, v199
	s_nop 1
	v_addc_co_u32_e32 v246, vcc, 0, v246, vcc
	v_cmp_le_u32_e32 vcc, 0x86, v199
	s_nop 1
	v_addc_co_u32_e32 v246, vcc, 0, v246, vcc
	v_cmp_le_u32_e32 vcc, 0xb6, v199
	s_nop 1
	v_addc_co_u32_e32 v246, vcc, 0, v246, vcc
	v_cmp_le_u32_e32 vcc, 0xf6, v199
	s_nop 1
	v_addc_co_u32_e32 v246, vcc, 0, v246, vcc
	v_cmp_le_u32_e32 vcc, 0x14c, v199
	s_nop 1
	v_addc_co_u32_e32 v246, vcc, 0, v246, vcc
	v_cmp_le_u32_e32 vcc, 0x1c2, v199
	s_nop 1
	v_addc_co_u32_e32 v246, vcc, 0, v246, vcc
	v_cmp_le_u32_e32 vcc, 0x261, v199
	s_nop 1
	v_addc_co_u32_e32 v246, vcc, 0, v246, vcc
	v_cmp_le_u32_e32 vcc, 0x339, v199
	s_nop 1
	v_addc_co_u32_e32 v246, vcc, 0, v246, vcc
	v_cmp_le_u32_e32 vcc, 0x45d, v199
	s_nop 1
	v_addc_co_u32_e32 v246, vcc, 0, v246, vcc
	v_cmp_le_u32_e32 vcc, 0x5e9, v199
	s_nop 1
	v_addc_co_u32_e32 v246, vcc, 0, v246, vcc
	v_cmp_gt_u32_e32 vcc, 16, v199
	s_nop 1
	v_cndmask_b32_e32 v246, v246, v199, vcc
	v_mul_u32_u24_e32 v107, 0xa0, v246
	v_lshlrev_b32_e32 v199, 4, v198
	v_mov_b32_e32 v246, 16
	v_cmp_le_u32_e32 vcc, 22, v199
	s_nop 1
	v_addc_co_u32_e32 v246, vcc, 0, v246, vcc
	v_cmp_le_u32_e32 vcc, 30, v199
	s_nop 1
	v_addc_co_u32_e32 v246, vcc, 0, v246, vcc
	v_cmp_le_u32_e32 vcc, 40, v199
	s_nop 1
	v_addc_co_u32_e32 v246, vcc, 0, v246, vcc
	v_cmp_le_u32_e32 vcc, 54, v199
	s_nop 1
	v_addc_co_u32_e32 v246, vcc, 0, v246, vcc
	v_cmp_le_u32_e32 vcc, 0x49, v199
	s_nop 1
	v_addc_co_u32_e32 v246, vcc, 0, v246, vcc
	v_cmp_le_u32_e32 vcc, 0x63, v199
	s_nop 1
	v_addc_co_u32_e32 v246, vcc, 0, v246, vcc
	v_cmp_le_u32_e32 vcc, 0x86, v199
	s_nop 1
	v_addc_co_u32_e32 v246, vcc, 0, v246, vcc
	v_cmp_le_u32_e32 vcc, 0xb6, v199
	s_nop 1
	v_addc_co_u32_e32 v246, vcc, 0, v246, vcc
	v_cmp_le_u32_e32 vcc, 0xf6, v199
	s_nop 1
	v_addc_co_u32_e32 v246, vcc, 0, v246, vcc
	v_cmp_le_u32_e32 vcc, 0x14c, v199
	s_nop 1
	v_addc_co_u32_e32 v246, vcc, 0, v246, vcc
	v_cmp_le_u32_e32 vcc, 0x1c2, v199
	s_nop 1
	v_addc_co_u32_e32 v246, vcc, 0, v246, vcc
	v_cmp_le_u32_e32 vcc, 0x261, v199
	s_nop 1
	v_addc_co_u32_e32 v246, vcc, 0, v246, vcc
	v_cmp_le_u32_e32 vcc, 0x339, v199
	s_nop 1
	v_addc_co_u32_e32 v246, vcc, 0, v246, vcc
	v_cmp_le_u32_e32 vcc, 0x45d, v199
	s_nop 1
	v_addc_co_u32_e32 v246, vcc, 0, v246, vcc
	v_cmp_le_u32_e32 vcc, 0x5e9, v199
	s_nop 1
	v_addc_co_u32_e32 v246, vcc, 0, v246, vcc
	v_cmp_gt_u32_e32 vcc, 16, v199
	s_nop 1
	v_cndmask_b32_e32 v246, v246, v199, vcc
	v_mul_u32_u24_e32 v108, 0xa0, v246
	s_mov_b32 s0, 0
	s_cmp_eq_u32 s45, 0x200
	s_cbranch_scc0 .Lattn_map_old1
	s_lshr_b32 s1, s44, 1
	s_and_b32 s3, s1, 7
	s_lshr_b32 s1, s1, 3
	s_and_b32 s63, s0, 3
	s_lshl_b32 s63, s63, 3
	s_lshr_b32 s68, s1, 3
	s_lshl_b32 s68, s68, 1
	s_add_i32 s63, s63, s68
	s_and_b32 s68, s44, 1
	s_add_i32 s63, s63, s68
	s_lshl_b32 s3, s3, 5
	s_add_i32 s63, s63, s3
	s_mul_i32 s63, s63, 3
	s_lshr_b32 s68, s0, 2
	s_min_u32 s68, s68, 2
	s_add_i32 s63, s63, s68
	s_and_b32 s1, s1, 7
	s_lshl_b32 s0, s63, 3
	s_or_b32 s0, s0, s1
	s_branch .Lattn_map_done1

; DI void phase_attn_a(int wv_, int vb_, int nvb_, char* ws_, const Ctx& p, char* smem) {
;     ...
;     const int u = (vb_ + k_ * nvb_ < 6144) ? vb_ + k_ * nvb_ : 6143;
;     const int head = u & 7, g = (u >> 3) % 3, rest = u / 24, idx = rest & 31, b = rest >> 5;
;     const int dil = (g == 0) ? 1 : ((g == 1) ? 4 : 16);
;     const int nbper = 32 / dil, r = idx / nbper, nb = idx % nbper;
;     u16* Og = (g == 0) ? (u16*)(ws_ + WS_H) : ((g == 1) ? (u16*)(ws_ + WS_H + 32 * MiB) : (u16*)(ws_ + WS_E));
;     float* lse = (float*)(ws_ + WS_LSE) + (size_t)g * NTOK * 8;
;     if (tid <= 128) sBias[tid] = p.rel_bias[t5_bucket(tid * dil) * 40 + g * 8 + head] * 1.4426950408889634f;
;     {
;       const int kk = tid; const int ksub = nb * 128 - 128 + kk;
;       bf16x8 v[8];
;       if (ksub >= 0) {
;         const u16* vp = P + ((size_t)b * SEQ + (size_t)ksub * dil + r) * 4608 + 3072 + g * 512 + head * 64;
; #pragma unroll
;         for (int i = 0; i < 8; ++i) v[i] = *(const bf16x8*)(vp + i * 8);
;       } else {
; #pragma unroll
;         for (int i = 0; i < 8; ++i) v[i] = zero8();
;       }
; #pragma unroll
;       for (int i = 0; i < 8; ++i)
; #pragma unroll
;         for (int jj = 0; jj < 8; ++jj) Vt[(i * 8 + jj) * 260 + kk] = (u16)v[i][jj];
;     }
;     __syncthreads();
;     {
;       const int qi = 32 * wave + c;
;       const int qtok = (nb * 128 + qi) * dil + r;
;       const u16* qp = P + ((size_t)b * SEQ + qtok) * 4608 + g * 512 + head * 64;
;       bf16x8 qf[4];
; #pragma unroll
;       for (int ks = 0; ks < 4; ++ks) qf[ks] = *(const bf16x8*)(qp + ks * 16 + h * 8);
;       float mx = -INFINITY, sum = 0.f;
;       f32x16 oacc[2]; oacc[0] = zero16(); oacc[1] = zero16();
; #pragma unroll 1
;       for (int kb = 0; kb < 5; ++kb) {
;         const int kk = 32 * wave + 32 * kb + c; const int ksub0 = nb * 128 - 128 + kk;
;         bf16x8 kf[4];
;         if (ksub0 >= 0) {
;           const u16* kp = P + ((size_t)b * SEQ + (size_t)ksub0 * dil + r) * 4608 + 1536 + g * 512 + head * 64;
; #pragma unroll
;           for (int ks = 0; ks < 4; ++ks) kf[ks] = *(const bf16x8*)(kp + ks * 16 + h * 8);
.Lattn_map_done1:
	s_min_i32 s0, s0, 0x17ff
	s_and_b32 s1, s0, 7
	s_lshr_b32 s3, s0, 3
	s_mul_hi_u32 s63, s3, 0xaaaaaaab
	s_lshr_b32 s63, s63, 1
	s_mul_i32 s68, s63, 3
	s_sub_i32 s62, s3, s68
	s_and_b32 s69, s63, 31
	s_lshr_b32 s70, s63, 5
	s_lshl_b32 s10, s62, 1
	s_sub_i32 s71, 5, s10
	s_lshr_b32 s11, s69, s71
	s_lshr_b32 s68, 32, s10
	s_add_i32 s68, s68, -1
	s_and_b32 s68, s69, s68
	s_lshl_b32 s12, s68, 7
	s_sub_i32 s71, 4, s60
	s_lshl_b32 s71, 1, s71
	s_add_i32 s71, s71, -1
	s_cmp_eq_u32 s68, 0
	s_cselect_b32 s13, s71, 0
	s_lshl_b32 s71, s62, 3
	s_add_i32 s71, s71, s1
	s_lshl_b32 s100, s71, 22
	s_lshl_b32 s101, s70, 19
	s_add_i32 s100, s100, s101
	s_add_u32 s8, s86, s100
	s_addc_u32 s9, s87, 0
	s_add_u32 s72, s8, 0x6000000
	s_addc_u32 s73, s9, 0
	s_add_u32 s74, s8, 0xc000000
	s_addc_u32 s75, s9, 0
	s_mov_b32 s100, 0x8600000
	s_cmp_eq_u32 s62, 0
	s_cselect_b32 s100, 0x6600000, s100
	s_cmp_eq_u32 s62, 2
	s_cselect_b32 s100, 0x1c600000, s100
	s_lshl_b32 s101, s70, 22
	s_add_i32 s100, s100, s101
	s_lshl_b32 s101, s1, 7
	s_add_i32 s100, s100, s101
	s_add_u32 s14, s78, s100
	s_addc_u32 s15, s79, 0
	s_lshl_b32 s100, s62, 20
	s_lshl_b32 s101, s70, 17
	s_add_i32 s100, s100, s101
	s_lshl_b32 s101, s1, 2
	s_add_i32 s100, s100, s101
	s_add_i32 s100, s100, 0x1e600000
	s_add_u32 s18, s78, s100
	s_addc_u32 s19, s79, 0
	s_lshl_b32 s61, s71, 2
	v_add_u32_e32 v231, s12, v200
	v_lshlrev_b32_e32 v196, s10, v231
	v_add_u32_e32 v196, s11, v196
	v_lshl_add_u32 v226, v196, 10, v239
	v_lshlrev_b32_e32 v228, 5, v196
	v_lshl_add_u32 v232, v196, 7, v201
	v_add_u32_e32 v246, s12, v240
	v_max_i32_e32 v98, 0, v246
	v_lshlrev_b32_e32 v98, s10, v98
	v_add_u32_e32 v98, s11, v98
	v_lshl_add_u32 v98, v98, 7, v241
	v_add_u32_e32 v99, 8, v246
	v_max_i32_e32 v99, 0, v99
	v_lshlrev_b32_e32 v99, s10, v99
	v_add_u32_e32 v99, s11, v99
	v_lshl_add_u32 v99, v99, 7, v241
	v_add_u32_e32 v100, 16, v246
	v_max_i32_e32 v100, 0, v100
	v_lshlrev_b32_e32 v100, s10, v100
	v_add_u32_e32 v100, s11, v100
	v_lshl_add_u32 v100, v100, 7, v241
	v_add_u32_e32 v101, 24, v246
	v_max_i32_e32 v101, 0, v101
	v_lshlrev_b32_e32 v101, s10, v101
	v_add_u32_e32 v101, s11, v101
	v_lshl_add_u32 v101, v101, 7, v241
	v_add_u32_e32 v102, 32, v246
	v_max_i32_e32 v102, 0, v102
	v_lshlrev_b32_e32 v102, s10, v102
	v_add_u32_e32 v102, s11, v102
	v_lshl_add_u32 v102, v102, 7, v241
	v_add_u32_e32 v103, 40, v246
	v_max_i32_e32 v103, 0, v103
	v_lshlrev_b32_e32 v103, s10, v103
	v_add_u32_e32 v103, s11, v103
	v_lshl_add_u32 v103, v103, 7, v241
	v_add_u32_e32 v104, 48, v246
	v_max_i32_e32 v104, 0, v104
	v_lshlrev_b32_e32 v104, s10, v104
	v_add_u32_e32 v104, s11, v104
	v_lshl_add_u32 v104, v104, 7, v241
	v_add_u32_e32 v105, 56, v246
	v_max_i32_e32 v105, 0, v105
	v_lshlrev_b32_e32 v105, s10, v105
	v_add_u32_e32 v105, s11, v105
	v_lshl_add_u32 v105, v105, 7, v241
	global_load_dwordx4 v[2:5], v98, s[72:73]
	global_load_dwordx4 v[6:9], v99, s[72:73]
	global_load_dwordx4 v[10:13], v100, s[72:73]
	global_load_dwordx4 v[14:17], v101, s[72:73]
	global_load_dwordx4 v[18:21], v102, s[72:73]
	global_load_dwordx4 v[22:25], v103, s[72:73]
	global_load_dwordx4 v[26:29], v104, s[72:73]
	global_load_dwordx4 v[30:33], v105, s[72:73]
	global_load_dwordx4 v[34:37], v98, s[74:75]
	global_load_dwordx4 v[38:41], v99, s[74:75]
	global_load_dwordx4 v[42:45], v100, s[74:75]
	global_load_dwordx4 v[46:49], v101, s[74:75]
	global_load_dwordx4 v[50:53], v102, s[74:75]
	global_load_dwordx4 v[54:57], v103, s[74:75]
	global_load_dwordx4 v[58:61], v104, s[74:75]
	global_load_dwordx4 v[62:65], v105, s[74:75]
	s_cmp_eq_u32 s62, 0
	s_cselect_b64 vcc, -1, 0
	v_cndmask_b32_e32 v196, v107, v106, vcc
	s_cmp_eq_u32 s62, 2
	s_cselect_b64 vcc, -1, 0
	v_cndmask_b32_e32 v196, v196, v108, vcc
	v_add_u32_e32 v196, s61, v196
	global_load_dword v229, v196, s[56:57]
	global_load_dwordx4 v[66:69], v232, s[8:9]
	global_load_dwordx4 v[70:73], v232, s[8:9] offset:32
	global_load_dwordx4 v[74:77], v232, s[8:9] offset:64
	global_load_dwordx4 v[78:81], v232, s[8:9] offset:96
	s_mov_b32 s34, 0
.Lattn_loop:
	s_cmp_eq_u32 s34, 0
	s_cbranch_scc1 .Lattn_w0
	s_waitcnt vmcnt(9)
	s_branch .Lattn_w1

; DI void phase_attn_a(int wv_, int vb_, int nvb_, char* ws_, const Ctx& p, char* smem) {
;     ...
;     if (tid <= 128) sBias[tid] = p.rel_bias[t5_bucket(tid * dil) * 40 + g * 8 + head] * 1.4426950408889634f;
;     {
;       const int kk = tid; const int ksub = nb * 128 - 128 + kk;
;       bf16x8 v[8];
;       if (ksub >= 0) {
;         const u16* vp = P + ((size_t)b * SEQ + (size_t)ksub * dil + r) * 4608 + 3072 + g * 512 + head * 64;
; #pragma unroll
;         for (int i = 0; i < 8; ++i) v[i] = *(const bf16x8*)(vp + i * 8);
;       } else {
; #pragma unroll
;         for (int i = 0; i < 8; ++i) v[i] = zero8();
;       }
; #pragma unroll
;       for (int i = 0; i < 8; ++i)
; #pragma unroll
;         for (int jj = 0; jj < 8; ++jj) Vt[(i * 8 + jj) * 260 + kk] = (u16)v[i][jj];
;     }
;     __syncthreads();
.Lattn_w1:
	s_barrier
	ds_write_b128 v203, v[2:5]
	ds_write_b128 v209, v[6:9] offset:1024
	ds_write_b128 v203, v[10:13] offset:2048
	ds_write_b128 v209, v[14:17] offset:3072
	ds_write_b128 v203, v[18:21] offset:4096
	ds_write_b128 v209, v[22:25] offset:5120
	ds_write_b128 v203, v[26:29] offset:6144
	ds_write_b128 v209, v[30:33] offset:7168
	ds_write_b128 v216, v[34:37]
	ds_write_b128 v216, v[38:41] offset:1024
	ds_write_b128 v216, v[42:45] offset:2048
	ds_write_b128 v216, v[46:49] offset:3072
	ds_write_b128 v216, v[50:53] offset:4096
	ds_write_b128 v216, v[54:57] offset:5120
	ds_write_b128 v216, v[58:61] offset:6144
	ds_write_b128 v216, v[62:65] offset:7168
	v_mul_f32_e32 v196, 0x3fb8aa3b, v229
	v_cndmask_b32_e64 v196, v207, v196, s[66:67]
	ds_write_b32 v224, v196
	s_mov_b32 s2, s13
	s_mov_b64 s[4:5], s[14:15]
	s_mov_b64 s[6:7], s[18:19]
	v_mov_b32_e32 v225, v226
	v_mov_b32_e32 v227, v228
	s_waitcnt lgkmcnt(0)
	s_barrier
	s_add_i32 s0, s34, 1
	s_cmp_eq_u32 s45, 0x200
	s_cbranch_scc0 .Lattn_map_old2
	s_lshr_b32 s1, s44, 1
	s_and_b32 s3, s1, 7
	s_lshr_b32 s1, s1, 3
	s_and_b32 s63, s0, 3
	s_lshl_b32 s63, s63, 3
	s_lshr_b32 s68, s1, 3
	s_lshl_b32 s68, s68, 1
	s_add_i32 s63, s63, s68
	s_and_b32 s68, s44, 1
	s_add_i32 s63, s63, s68
	s_lshl_b32 s3, s3, 5
	s_add_i32 s63, s63, s3
	s_mul_i32 s63, s63, 3
	s_lshr_b32 s68, s0, 2
	s_min_u32 s68, s68, 2
	s_add_i32 s63, s63, s68
	s_and_b32 s1, s1, 7
	s_lshl_b32 s0, s63, 3
	s_or_b32 s0, s0, s1
	s_branch .Lattn_map_done2

; DI void phase_attn_a(int wv_, int vb_, int nvb_, char* ws_, const Ctx& p, char* smem) {
;     ...
;     const int u = (vb_ + k_ * nvb_ < 6144) ? vb_ + k_ * nvb_ : 6143;
;     const int head = u & 7, g = (u >> 3) % 3, rest = u / 24, idx = rest & 31, b = rest >> 5;
;     const int dil = (g == 0) ? 1 : ((g == 1) ? 4 : 16);
;     const int nbper = 32 / dil, r = idx / nbper, nb = idx % nbper;
;     u16* Og = (g == 0) ? (u16*)(ws_ + WS_H) : ((g == 1) ? (u16*)(ws_ + WS_H + 32 * MiB) : (u16*)(ws_ + WS_E));
;     float* lse = (float*)(ws_ + WS_LSE) + (size_t)g * NTOK * 8;
;     if (tid <= 128) sBias[tid] = p.rel_bias[t5_bucket(tid * dil) * 40 + g * 8 + head] * 1.4426950408889634f;
;     {
;       const int kk = tid; const int ksub = nb * 128 - 128 + kk;
;       bf16x8 v[8];
;       if (ksub >= 0) {
;         const u16* vp = P + ((size_t)b * SEQ + (size_t)ksub * dil + r) * 4608 + 3072 + g * 512 + head * 64;
; #pragma unroll
;         for (int i = 0; i < 8; ++i) v[i] = *(const bf16x8*)(vp + i * 8);
;       } else {
; #pragma unroll
;         for (int i = 0; i < 8; ++i) v[i] = zero8();
;       }
; #pragma unroll
;       for (int i = 0; i < 8; ++i)
; #pragma unroll
;         for (int jj = 0; jj < 8; ++jj) Vt[(i * 8 + jj) * 260 + kk] = (u16)v[i][jj];
;     }
;     __syncthreads();
;     {
;       const int qi = 32 * wave + c;
;       const int qtok = (nb * 128 + qi) * dil + r;
;       const u16* qp = P + ((size_t)b * SEQ + qtok) * 4608 + g * 512 + head * 64;
;       bf16x8 qf[4];
; #pragma unroll
;       for (int ks = 0; ks < 4; ++ks) qf[ks] = *(const bf16x8*)(qp + ks * 16 + h * 8);
;       float mx = -INFINITY, sum = 0.f;
;       f32x16 oacc[2]; oacc[0] = zero16(); oacc[1] = zero16();
; #pragma unroll 1
;       for (int kb = 0; kb < 5; ++kb) {
;         const int kk = 32 * wave + 32 * kb + c; const int ksub0 = nb * 128 - 128 + kk;
;         bf16x8 kf[4];
;         if (ksub0 >= 0) {
;           const u16* kp = P + ((size_t)b * SEQ + (size_t)ksub0 * dil + r) * 4608 + 1536 + g * 512 + head * 64;
; #pragma unroll
;           for (int ks = 0; ks < 4; ++ks) kf[ks] = *(const bf16x8*)(kp + ks * 16 + h * 8);
;         } else {
; #pragma unroll
;           for (int ks = 0; ks < 4; ++ks) kf[ks] = zero8();
;         }
;         f32x16 sa = zero16();
.Lattn_map_done2:
	s_min_i32 s0, s0, 0x17ff
	s_and_b32 s1, s0, 7
	s_lshr_b32 s3, s0, 3
	s_mul_hi_u32 s63, s3, 0xaaaaaaab
	s_lshr_b32 s63, s63, 1
	s_mul_i32 s68, s63, 3
	s_sub_i32 s62, s3, s68
	s_and_b32 s69, s63, 31
	s_lshr_b32 s70, s63, 5
	s_lshl_b32 s10, s62, 1
	s_sub_i32 s71, 5, s10
	s_lshr_b32 s11, s69, s71
	s_lshr_b32 s68, 32, s10
	s_add_i32 s68, s68, -1
	s_and_b32 s68, s69, s68
	s_lshl_b32 s12, s68, 7
	s_sub_i32 s71, 4, s60
	s_lshl_b32 s71, 1, s71
	s_add_i32 s71, s71, -1
	s_cmp_eq_u32 s68, 0
	s_cselect_b32 s13, s71, 0
	s_lshl_b32 s71, s62, 3
	s_add_i32 s71, s71, s1
	s_lshl_b32 s100, s71, 22
	s_lshl_b32 s101, s70, 19
	s_add_i32 s100, s100, s101
	s_add_u32 s8, s86, s100
	s_addc_u32 s9, s87, 0
	s_add_u32 s72, s8, 0x6000000
	s_addc_u32 s73, s9, 0
	s_add_u32 s74, s8, 0xc000000
	s_addc_u32 s75, s9, 0
	s_mov_b32 s100, 0x8600000
	s_cmp_eq_u32 s62, 0
	s_cselect_b32 s100, 0x6600000, s100
	s_cmp_eq_u32 s62, 2
	s_cselect_b32 s100, 0x1c600000, s100
	s_lshl_b32 s101, s70, 22
	s_add_i32 s100, s100, s101
	s_lshl_b32 s101, s1, 7
	s_add_i32 s100, s100, s101
	s_add_u32 s14, s78, s100
	s_addc_u32 s15, s79, 0
	s_lshl_b32 s100, s62, 20
	s_lshl_b32 s101, s70, 17
	s_add_i32 s100, s100, s101
	s_lshl_b32 s101, s1, 2
	s_add_i32 s100, s100, s101
	s_add_i32 s100, s100, 0x1e600000
	s_add_u32 s18, s78, s100
	s_addc_u32 s19, s79, 0
	s_lshl_b32 s61, s71, 2
	v_add_u32_e32 v231, s12, v200
	v_lshlrev_b32_e32 v196, s10, v231
	v_add_u32_e32 v196, s11, v196
	v_lshl_add_u32 v226, v196, 10, v239
	v_lshlrev_b32_e32 v228, 5, v196
	v_lshl_add_u32 v232, v196, 7, v201
	v_add_u32_e32 v246, s12, v240
	v_max_i32_e32 v98, 0, v246
	v_lshlrev_b32_e32 v98, s10, v98
	v_add_u32_e32 v98, s11, v98
	v_lshl_add_u32 v98, v98, 7, v241
	v_add_u32_e32 v99, 8, v246
	v_max_i32_e32 v99, 0, v99
	v_lshlrev_b32_e32 v99, s10, v99
	v_add_u32_e32 v99, s11, v99
	v_lshl_add_u32 v99, v99, 7, v241
	v_add_u32_e32 v100, 16, v246
	v_max_i32_e32 v100, 0, v100
	v_lshlrev_b32_e32 v100, s10, v100
	v_add_u32_e32 v100, s11, v100
	v_lshl_add_u32 v100, v100, 7, v241
	v_add_u32_e32 v101, 24, v246
	v_max_i32_e32 v101, 0, v101
	v_lshlrev_b32_e32 v101, s10, v101
	v_add_u32_e32 v101, s11, v101
	v_lshl_add_u32 v101, v101, 7, v241
	v_add_u32_e32 v102, 32, v246
	v_max_i32_e32 v102, 0, v102
	v_lshlrev_b32_e32 v102, s10, v102
	v_add_u32_e32 v102, s11, v102
	v_lshl_add_u32 v102, v102, 7, v241
	v_add_u32_e32 v103, 40, v246
	v_max_i32_e32 v103, 0, v103
	v_lshlrev_b32_e32 v103, s10, v103
	v_add_u32_e32 v103, s11, v103
	v_lshl_add_u32 v103, v103, 7, v241
	v_add_u32_e32 v104, 48, v246
	v_max_i32_e32 v104, 0, v104
	v_lshlrev_b32_e32 v104, s10, v104
	v_add_u32_e32 v104, s11, v104
	v_lshl_add_u32 v104, v104, 7, v241
	v_add_u32_e32 v105, 56, v246
	v_max_i32_e32 v105, 0, v105
	v_lshlrev_b32_e32 v105, s10, v105
	v_add_u32_e32 v105, s11, v105
	v_lshl_add_u32 v105, v105, 7, v241
	global_load_dwordx4 v[2:5], v98, s[72:73]
	global_load_dwordx4 v[6:9], v99, s[72:73]
	global_load_dwordx4 v[10:13], v100, s[72:73]
	global_load_dwordx4 v[14:17], v101, s[72:73]
	global_load_dwordx4 v[18:21], v102, s[72:73]
	global_load_dwordx4 v[22:25], v103, s[72:73]
	global_load_dwordx4 v[26:29], v104, s[72:73]
	global_load_dwordx4 v[30:33], v105, s[72:73]
	global_load_dwordx4 v[34:37], v98, s[74:75]
	global_load_dwordx4 v[38:41], v99, s[74:75]
	global_load_dwordx4 v[42:45], v100, s[74:75]
	global_load_dwordx4 v[46:49], v101, s[74:75]
	global_load_dwordx4 v[50:53], v102, s[74:75]
	global_load_dwordx4 v[54:57], v103, s[74:75]
	global_load_dwordx4 v[58:61], v104, s[74:75]
	global_load_dwordx4 v[62:65], v105, s[74:75]
	s_cmp_eq_u32 s62, 0
	s_cselect_b64 vcc, -1, 0
	v_cndmask_b32_e32 v196, v107, v106, vcc
	s_cmp_eq_u32 s62, 2
	s_cselect_b64 vcc, -1, 0
	v_cndmask_b32_e32 v196, v196, v108, vcc
	v_add_u32_e32 v196, s61, v196
	global_load_dword v229, v196, s[56:57]
	v_mov_b32_e32 v194, v207
	v_mov_b32_e32 v195, 0
	v_mov_b32_e32 v146, 0
	v_mov_b32_e32 v147, 0
	v_mov_b32_e32 v148, 0
	v_mov_b32_e32 v149, 0
	v_mov_b32_e32 v150, 0
	v_mov_b32_e32 v151, 0
	v_mov_b32_e32 v152, 0
	v_mov_b32_e32 v153, 0
	v_mov_b32_e32 v154, 0
	v_mov_b32_e32 v155, 0
	v_mov_b32_e32 v156, 0
	v_mov_b32_e32 v157, 0
	v_mov_b32_e32 v158, 0
	v_mov_b32_e32 v159, 0
	v_mov_b32_e32 v160, 0
	v_mov_b32_e32 v161, 0
	v_mov_b32_e32 v162, 0
	v_mov_b32_e32 v163, 0
	v_mov_b32_e32 v164, 0
	v_mov_b32_e32 v165, 0
	v_mov_b32_e32 v166, 0
	v_mov_b32_e32 v167, 0
	v_mov_b32_e32 v168, 0
	v_mov_b32_e32 v169, 0
	v_mov_b32_e32 v170, 0
	v_mov_b32_e32 v171, 0
	v_mov_b32_e32 v172, 0
	v_mov_b32_e32 v173, 0
	v_mov_b32_e32 v174, 0
	v_mov_b32_e32 v175, 0
	v_mov_b32_e32 v176, 0
	v_mov_b32_e32 v177, 0
	s_bitcmp1_b32 s2, 0
	s_cbranch_scc1 .Lattn_end0
; DI void phase_attn_a(int wv_, int vb_, int nvb_, char* ws_, const Ctx& p, char* smem) {
;     ...
;         const int kk = 32 * wave + 32 * kb + c; const int ksub0 = nb * 128 - 128 + kk;
;         bf16x8 kf[4];
;         if (ksub0 >= 0) {
;           const u16* kp = P + ((size_t)b * SEQ + (size_t)ksub0 * dil + r) * 4608 + 1536 + g * 512 + head * 64;
; #pragma unroll
;           for (int ks = 0; ks < 4; ++ks) kf[ks] = *(const bf16x8*)(kp + ks * 16 + h * 8);
;         } else {
; #pragma unroll
;           for (int ks = 0; ks < 4; ++ks) kf[ks] = zero8();
;         }
;         f32x16 sa = zero16();
; #pragma unroll
;         for (int ks = 0; ks < 4; ++ks) sa = MFMA32(kf[ks], qf[ks], sa);
;         float bm = -INFINITY;
;         const int sbase = c + 128 - 32 * kb - 4 * h;
;         const unsigned slim = (unsigned)((nb * 128 + 32 * wave + c) < 128 ? (nb * 128 + 32 * wave + c) : 128);
;         if (nb > 0 && kb >= 1 && kb <= 3) {
; #pragma unroll
;           for (int i = 0; i < 16; ++i) {
;             const int step = sbase - ((i & 3) + 8 * (i >> 2));
;             const float v = sa[i] + sBias[step];
;             sa[i] = v; bm = fmaxf(bm, v);
;           }
;         } else {
; #pragma unroll
;           for (int i = 0; i < 16; ++i) {
;             const int step = sbase - ((i & 3) + 8 * (i >> 2));
;             const bool valid = (unsigned)step <= slim;
;             const float bv = sBias[step];
;             float v = valid ? sa[i] + bv : -INFINITY;
;             sa[i] = v; bm = fmaxf(bm, v);
;           }
;         }
;         bm = fmaxf(bm, shx(bm, 32));
;         const float mnew = fmaxf(mx, bm);
;         const float mref = (mnew == -INFINITY) ? 0.f : mnew;
;         const float scale = __builtin_amdgcn_exp2f(mx - mref);
;         float ps = 0.f;
; #pragma unroll
;         for (int i = 0; i < 16; ++i) { float pv = __builtin_amdgcn_exp2f(sa[i] - mref); sa[i] = pv; ps += pv; }
;         sum = sum * scale + ps; mx = mnew;
; #pragma unroll
;         for (int i = 0; i < 16; ++i) { oacc[0][i] *= scale; oacc[1][i] *= scale; }
; #pragma unroll
;         for (int s = 0; s < 2; ++s) {
;           bf16x8 pb = pack8(sa, s);
;           const int keybase = 32 * wave + 32 * kb + 16 * s;
; #pragma unroll
;           for (int mb = 0; mb < 2; ++mb) {
;             const u16* vr = Vt + (mb * 32 + c) * 260 + keybase + 4 * h;
	ds_read_b128 v[82:85], v217
	ds_read_b128 v[86:89], v218
	ds_read_b128 v[90:93], v219
	ds_read_b128 v[94:97], v220
	ds_read2_b32 v[178:179], v223 offset0:159 offset1:158
	ds_read2_b32 v[180:181], v223 offset0:157 offset1:156
	ds_read2_b32 v[182:183], v223 offset0:151 offset1:150
	ds_read2_b32 v[184:185], v223 offset0:149 offset1:148
	ds_read2_b32 v[186:187], v223 offset0:143 offset1:142
	ds_read2_b32 v[188:189], v223 offset0:141 offset1:140
	ds_read2_b32 v[190:191], v223 offset0:135 offset1:134
	ds_read2_b32 v[192:193], v223 offset0:133 offset1:132
	s_waitcnt lgkmcnt(11)
	v_mfma_f32_32x32x16_bf16 v[130:145], v[82:85], v[66:69], 0
	s_waitcnt lgkmcnt(10)
	v_mfma_f32_32x32x16_bf16 v[130:145], v[86:89], v[70:73], v[130:145]
	s_waitcnt lgkmcnt(9)
	v_mfma_f32_32x32x16_bf16 v[130:145], v[90:93], v[74:77], v[130:145]
	s_waitcnt lgkmcnt(8)
	v_mfma_f32_32x32x16_bf16 v[130:145], v[94:97], v[78:81], v[130:145]
	s_waitcnt lgkmcnt(0)
	s_nop 7
	s_nop 3
	v_add_f32_e32 v130, v130, v178
	v_add_f32_e32 v131, v131, v179
	v_add_f32_e32 v132, v132, v180
	v_add_f32_e32 v133, v133, v181
	v_add_f32_e32 v134, v134, v182
	v_add_f32_e32 v135, v135, v183
	v_add_f32_e32 v136, v136, v184
	v_add_f32_e32 v137, v137, v185
	v_add_f32_e32 v138, v138, v186
	v_add_f32_e32 v139, v139, v187
	v_add_f32_e32 v140, v140, v188
	v_add_f32_e32 v141, v141, v189
	v_add_f32_e32 v142, v142, v190
	v_add_f32_e32 v143, v143, v191
	v_add_f32_e32 v144, v144, v192
	v_add_f32_e32 v145, v145, v193
	ds_read_b64_tr_b16 v[178:179], v221
	ds_read_b64_tr_b16 v[180:181], v221 offset:1024
	ds_read_b64_tr_b16 v[182:183], v222
	ds_read_b64_tr_b16 v[184:185], v222 offset:1024
	ds_read_b64_tr_b16 v[186:187], v221 offset:2048
	ds_read_b64_tr_b16 v[188:189], v221 offset:3072
	ds_read_b64_tr_b16 v[190:191], v222 offset:2048
	ds_read_b64_tr_b16 v[192:193], v222 offset:3072
	v_max3_f32 v235, v130, v131, v132
	v_max3_f32 v235, v235, v133, v134
	v_max3_f32 v235, v235, v135, v136
	v_max3_f32 v235, v235, v137, v138
	v_max3_f32 v235, v235, v139, v140
	v_max3_f32 v235, v235, v141, v142
	v_max3_f32 v235, v235, v143, v144
	v_max_f32_e32 v235, v235, v145
	v_mov_b32_e32 v196, v235
	s_nop 1
	v_permlane32_swap_b32_e32 v196, v235
	v_max_f32_e32 v235, v235, v196
	v_max_f32_e32 v234, v194, v235
	v_cmp_eq_f32_e32 vcc, 0xff800000, v234
	s_nop 1
	v_cndmask_b32_e64 v237, v234, 0, vcc
	v_sub_f32_e32 v196, v194, v237
	v_exp_f32_e32 v233, v196
	v_sub_f32_e32 v130, v130, v237
	v_sub_f32_e32 v131, v131, v237
	v_sub_f32_e32 v132, v132, v237
	v_sub_f32_e32 v133, v133, v237
	v_sub_f32_e32 v134, v134, v237
	v_sub_f32_e32 v135, v135, v237
	v_sub_f32_e32 v136, v136, v237
	v_sub_f32_e32 v137, v137, v237
	v_sub_f32_e32 v138, v138, v237
	v_sub_f32_e32 v139, v139, v237
	v_sub_f32_e32 v140, v140, v237
	v_sub_f32_e32 v141, v141, v237
	v_sub_f32_e32 v142, v142, v237
	v_sub_f32_e32 v143, v143, v237
	v_sub_f32_e32 v144, v144, v237
	v_sub_f32_e32 v145, v145, v237
	v_exp_f32_e32 v130, v130
	v_exp_f32_e32 v131, v131
	v_exp_f32_e32 v132, v132
	v_exp_f32_e32 v133, v133
	v_exp_f32_e32 v134, v134
	v_exp_f32_e32 v135, v135
	v_exp_f32_e32 v136, v136
	v_exp_f32_e32 v137, v137
	v_exp_f32_e32 v138, v138
	v_exp_f32_e32 v139, v139
	v_exp_f32_e32 v140, v140
	v_exp_f32_e32 v141, v141
	v_exp_f32_e32 v142, v142
	v_exp_f32_e32 v143, v143
	v_exp_f32_e32 v144, v144
	v_exp_f32_e32 v145, v145
	v_mov_b32_e32 v194, v234
	v_add_f32_e32 v236, v130, v131
	v_add_f32_e32 v236, v236, v132
	v_add_f32_e32 v236, v236, v133
	v_add_f32_e32 v236, v236, v134
	v_add_f32_e32 v236, v236, v135
	v_add_f32_e32 v236, v236, v136
	v_add_f32_e32 v236, v236, v137
	v_add_f32_e32 v236, v236, v138
	v_add_f32_e32 v236, v236, v139
	v_add_f32_e32 v236, v236, v140
	v_add_f32_e32 v236, v236, v141
	v_add_f32_e32 v236, v236, v142
	v_add_f32_e32 v236, v236, v143
	v_add_f32_e32 v236, v236, v144
	v_add_f32_e32 v236, v236, v145
	v_fma_f32 v195, v195, v233, v236
	v_mul_f32_e32 v146, v233, v146
	v_mul_f32_e32 v147, v233, v147
	v_mul_f32_e32 v148, v233, v148
	v_mul_f32_e32 v149, v233, v149
	v_mul_f32_e32 v150, v233, v150
	v_mul_f32_e32 v151, v233, v151
	v_mul_f32_e32 v152, v233, v152
	v_mul_f32_e32 v153, v233, v153
	v_mul_f32_e32 v154, v233, v154
	v_mul_f32_e32 v155, v233, v155
	v_mul_f32_e32 v156, v233, v156
	v_mul_f32_e32 v157, v233, v157
	v_mul_f32_e32 v158, v233, v158
	v_mul_f32_e32 v159, v233, v159
	v_mul_f32_e32 v160, v233, v160
	v_mul_f32_e32 v161, v233, v161
	v_mul_f32_e32 v162, v233, v162
	v_mul_f32_e32 v163, v233, v163
	v_mul_f32_e32 v164, v233, v164
	v_mul_f32_e32 v165, v233, v165
	v_mul_f32_e32 v166, v233, v166
	v_mul_f32_e32 v167, v233, v167
	v_mul_f32_e32 v168, v233, v168
	v_mul_f32_e32 v169, v233, v169
	v_mul_f32_e32 v170, v233, v170
	v_mul_f32_e32 v171, v233, v171
	v_mul_f32_e32 v172, v233, v172
	v_mul_f32_e32 v173, v233, v173
	v_mul_f32_e32 v174, v233, v174
	v_mul_f32_e32 v175, v233, v175
	v_mul_f32_e32 v176, v233, v176
	v_mul_f32_e32 v177, v233, v177
	v_cvt_pk_bf16_f32 v130, v130, v131
	v_cvt_pk_bf16_f32 v131, v132, v133
	v_cvt_pk_bf16_f32 v132, v134, v135
	v_cvt_pk_bf16_f32 v133, v136, v137
	v_cvt_pk_bf16_f32 v134, v138, v139
	v_cvt_pk_bf16_f32 v135, v140, v141
	v_cvt_pk_bf16_f32 v136, v142, v143
	v_cvt_pk_bf16_f32 v137, v144, v145
	s_waitcnt lgkmcnt(0)
	s_nop 1
	v_mfma_f32_32x32x16_bf16 v[146:161], v[178:181], v[130:133], v[146:161]
	v_mfma_f32_32x32x16_bf16 v[162:177], v[182:185], v[130:133], v[162:177]
	v_mfma_f32_32x32x16_bf16 v[146:161], v[186:189], v[134:137], v[146:161]
	v_mfma_f32_32x32x16_bf16 v[162:177], v[190:193], v[134:137], v[162:177]
; DI void phase_attn_a(int wv_, int vb_, int nvb_, char* ws_, const Ctx& p, char* smem) {
;     ...
;         const int kk = 32 * wave + 32 * kb + c; const int ksub0 = nb * 128 - 128 + kk;
;         bf16x8 kf[4];
;         if (ksub0 >= 0) {
;           const u16* kp = P + ((size_t)b * SEQ + (size_t)ksub0 * dil + r) * 4608 + 1536 + g * 512 + head * 64;
; #pragma unroll
;           for (int ks = 0; ks < 4; ++ks) kf[ks] = *(const bf16x8*)(kp + ks * 16 + h * 8);
;         } else {
; #pragma unroll
;           for (int ks = 0; ks < 4; ++ks) kf[ks] = zero8();
;         }
;         f32x16 sa = zero16();
; #pragma unroll
;         for (int ks = 0; ks < 4; ++ks) sa = MFMA32(kf[ks], qf[ks], sa);
;         float bm = -INFINITY;
;         const int sbase = c + 128 - 32 * kb - 4 * h;
;         const unsigned slim = (unsigned)((nb * 128 + 32 * wave + c) < 128 ? (nb * 128 + 32 * wave + c) : 128);
;         if (nb > 0 && kb >= 1 && kb <= 3) {
; #pragma unroll
;           for (int i = 0; i < 16; ++i) {
;             const int step = sbase - ((i & 3) + 8 * (i >> 2));
;             const float v = sa[i] + sBias[step];
;             sa[i] = v; bm = fmaxf(bm, v);
;           }
;         } else {
; #pragma unroll
;           for (int i = 0; i < 16; ++i) {
;             const int step = sbase - ((i & 3) + 8 * (i >> 2));
;             const bool valid = (unsigned)step <= slim;
;             const float bv = sBias[step];
;             float v = valid ? sa[i] + bv : -INFINITY;
;             sa[i] = v; bm = fmaxf(bm, v);
;           }
;         }
;         bm = fmaxf(bm, shx(bm, 32));
;         const float mnew = fmaxf(mx, bm);
;         const float mref = (mnew == -INFINITY) ? 0.f : mnew;
;         const float scale = __builtin_amdgcn_exp2f(mx - mref);
;         float ps = 0.f;
; #pragma unroll
;         for (int i = 0; i < 16; ++i) { float pv = __builtin_amdgcn_exp2f(sa[i] - mref); sa[i] = pv; ps += pv; }
;         sum = sum * scale + ps; mx = mnew;
; #pragma unroll
;         for (int i = 0; i < 16; ++i) { oacc[0][i] *= scale; oacc[1][i] *= scale; }
; #pragma unroll
;         for (int s = 0; s < 2; ++s) {
;           bf16x8 pb = pack8(sa, s);
;           const int keybase = 32 * wave + 32 * kb + 16 * s;
; #pragma unroll
;           for (int mb = 0; mb < 2; ++mb) {
;             const u16* vr = Vt + (mb * 32 + c) * 260 + keybase + 4 * h;
.Lattn_end0:
	s_bitcmp1_b32 s2, 1
	s_cbranch_scc1 .Lattn_end1
	ds_read_b128 v[82:85], v217 offset:4096
	ds_read_b128 v[86:89], v218 offset:4096
	ds_read_b128 v[90:93], v219 offset:4096
	ds_read_b128 v[94:97], v220 offset:4096
	ds_read2_b32 v[178:179], v223 offset0:127 offset1:126
	ds_read2_b32 v[180:181], v223 offset0:125 offset1:124
	ds_read2_b32 v[182:183], v223 offset0:119 offset1:118
	ds_read2_b32 v[184:185], v223 offset0:117 offset1:116
	ds_read2_b32 v[186:187], v223 offset0:111 offset1:110
	ds_read2_b32 v[188:189], v223 offset0:109 offset1:108
	ds_read2_b32 v[190:191], v223 offset0:103 offset1:102
	ds_read2_b32 v[192:193], v223 offset0:101 offset1:100
	s_waitcnt lgkmcnt(11)
	v_mfma_f32_32x32x16_bf16 v[130:145], v[82:85], v[66:69], 0
	s_waitcnt lgkmcnt(10)
	v_mfma_f32_32x32x16_bf16 v[130:145], v[86:89], v[70:73], v[130:145]
	s_waitcnt lgkmcnt(9)
	v_mfma_f32_32x32x16_bf16 v[130:145], v[90:93], v[74:77], v[130:145]
	s_waitcnt lgkmcnt(8)
	v_mfma_f32_32x32x16_bf16 v[130:145], v[94:97], v[78:81], v[130:145]
	s_waitcnt lgkmcnt(0)
	s_nop 7
	s_nop 3
	v_add_f32_e32 v130, v130, v178
	v_add_f32_e32 v131, v131, v179
	v_add_f32_e32 v132, v132, v180
	v_add_f32_e32 v133, v133, v181
	v_add_f32_e32 v134, v134, v182
	v_add_f32_e32 v135, v135, v183
	v_add_f32_e32 v136, v136, v184
	v_add_f32_e32 v137, v137, v185
	v_add_f32_e32 v138, v138, v186
	v_add_f32_e32 v139, v139, v187
	v_add_f32_e32 v140, v140, v188
	v_add_f32_e32 v141, v141, v189
	v_add_f32_e32 v142, v142, v190
	v_add_f32_e32 v143, v143, v191
	v_add_f32_e32 v144, v144, v192
	v_add_f32_e32 v145, v145, v193
	ds_read_b64_tr_b16 v[178:179], v221 offset:4096
	ds_read_b64_tr_b16 v[180:181], v221 offset:5120
	ds_read_b64_tr_b16 v[182:183], v222 offset:4096
	ds_read_b64_tr_b16 v[184:185], v222 offset:5120
	ds_read_b64_tr_b16 v[186:187], v221 offset:6144
	ds_read_b64_tr_b16 v[188:189], v221 offset:7168
	ds_read_b64_tr_b16 v[190:191], v222 offset:6144
	ds_read_b64_tr_b16 v[192:193], v222 offset:7168
	v_max3_f32 v235, v130, v131, v132
	v_max3_f32 v235, v235, v133, v134
	v_max3_f32 v235, v235, v135, v136
	v_max3_f32 v235, v235, v137, v138
	v_max3_f32 v235, v235, v139, v140
	v_max3_f32 v235, v235, v141, v142
	v_max3_f32 v235, v235, v143, v144
	v_max_f32_e32 v235, v235, v145
	v_mov_b32_e32 v196, v235
	s_nop 1
	v_permlane32_swap_b32_e32 v196, v235
	v_max_f32_e32 v235, v235, v196
	v_max_f32_e32 v234, v194, v235
	v_cmp_eq_f32_e32 vcc, 0xff800000, v234
	s_nop 1
	v_cndmask_b32_e64 v237, v234, 0, vcc
	v_sub_f32_e32 v196, v194, v237
	v_exp_f32_e32 v233, v196
	v_sub_f32_e32 v130, v130, v237
	v_sub_f32_e32 v131, v131, v237
	v_sub_f32_e32 v132, v132, v237
	v_sub_f32_e32 v133, v133, v237
	v_sub_f32_e32 v134, v134, v237
	v_sub_f32_e32 v135, v135, v237
	v_sub_f32_e32 v136, v136, v237
	v_sub_f32_e32 v137, v137, v237
	v_sub_f32_e32 v138, v138, v237
	v_sub_f32_e32 v139, v139, v237
	v_sub_f32_e32 v140, v140, v237
	v_sub_f32_e32 v141, v141, v237
	v_sub_f32_e32 v142, v142, v237
	v_sub_f32_e32 v143, v143, v237
	v_sub_f32_e32 v144, v144, v237
	v_sub_f32_e32 v145, v145, v237
	v_exp_f32_e32 v130, v130
	v_exp_f32_e32 v131, v131
	v_exp_f32_e32 v132, v132
	v_exp_f32_e32 v133, v133
	v_exp_f32_e32 v134, v134
	v_exp_f32_e32 v135, v135
	v_exp_f32_e32 v136, v136
	v_exp_f32_e32 v137, v137
	v_exp_f32_e32 v138, v138
	v_exp_f32_e32 v139, v139
	v_exp_f32_e32 v140, v140
	v_exp_f32_e32 v141, v141
	v_exp_f32_e32 v142, v142
	v_exp_f32_e32 v143, v143
	v_exp_f32_e32 v144, v144
	v_exp_f32_e32 v145, v145
	v_mov_b32_e32 v194, v234
	v_add_f32_e32 v236, v130, v131
	v_add_f32_e32 v236, v236, v132
	v_add_f32_e32 v236, v236, v133
	v_add_f32_e32 v236, v236, v134
	v_add_f32_e32 v236, v236, v135
	v_add_f32_e32 v236, v236, v136
	v_add_f32_e32 v236, v236, v137
	v_add_f32_e32 v236, v236, v138
	v_add_f32_e32 v236, v236, v139
	v_add_f32_e32 v236, v236, v140
	v_add_f32_e32 v236, v236, v141
	v_add_f32_e32 v236, v236, v142
	v_add_f32_e32 v236, v236, v143
	v_add_f32_e32 v236, v236, v144
	v_add_f32_e32 v236, v236, v145
	v_fma_f32 v195, v195, v233, v236
	v_mul_f32_e32 v146, v233, v146
	v_mul_f32_e32 v147, v233, v147
	v_mul_f32_e32 v148, v233, v148
	v_mul_f32_e32 v149, v233, v149
	v_mul_f32_e32 v150, v233, v150
	v_mul_f32_e32 v151, v233, v151
	v_mul_f32_e32 v152, v233, v152
	v_mul_f32_e32 v153, v233, v153
	v_mul_f32_e32 v154, v233, v154
	v_mul_f32_e32 v155, v233, v155
	v_mul_f32_e32 v156, v233, v156
	v_mul_f32_e32 v157, v233, v157
	v_mul_f32_e32 v158, v233, v158
	v_mul_f32_e32 v159, v233, v159
	v_mul_f32_e32 v160, v233, v160
	v_mul_f32_e32 v161, v233, v161
	v_mul_f32_e32 v162, v233, v162
	v_mul_f32_e32 v163, v233, v163
	v_mul_f32_e32 v164, v233, v164
	v_mul_f32_e32 v165, v233, v165
	v_mul_f32_e32 v166, v233, v166
	v_mul_f32_e32 v167, v233, v167
	v_mul_f32_e32 v168, v233, v168
	v_mul_f32_e32 v169, v233, v169
	v_mul_f32_e32 v170, v233, v170
	v_mul_f32_e32 v171, v233, v171
	v_mul_f32_e32 v172, v233, v172
	v_mul_f32_e32 v173, v233, v173
	v_mul_f32_e32 v174, v233, v174
	v_mul_f32_e32 v175, v233, v175
	v_mul_f32_e32 v176, v233, v176
	v_mul_f32_e32 v177, v233, v177
	v_cvt_pk_bf16_f32 v130, v130, v131
	v_cvt_pk_bf16_f32 v131, v132, v133
	v_cvt_pk_bf16_f32 v132, v134, v135
	v_cvt_pk_bf16_f32 v133, v136, v137
	v_cvt_pk_bf16_f32 v134, v138, v139
	v_cvt_pk_bf16_f32 v135, v140, v141
	v_cvt_pk_bf16_f32 v136, v142, v143
	v_cvt_pk_bf16_f32 v137, v144, v145
	s_waitcnt lgkmcnt(0)
	s_nop 1
	v_mfma_f32_32x32x16_bf16 v[146:161], v[178:181], v[130:133], v[146:161]
	v_mfma_f32_32x32x16_bf16 v[162:177], v[182:185], v[130:133], v[162:177]
	v_mfma_f32_32x32x16_bf16 v[146:161], v[186:189], v[134:137], v[146:161]
	v_mfma_f32_32x32x16_bf16 v[162:177], v[190:193], v[134:137], v[162:177]
; DI void phase_attn_a(int wv_, int vb_, int nvb_, char* ws_, const Ctx& p, char* smem) {
;     ...
;       for (int kb = 0; kb < 5; ++kb) {
;         const int kk = 32 * wave + 32 * kb + c; const int ksub0 = nb * 128 - 128 + kk;
;         bf16x8 kf[4];
;         if (ksub0 >= 0) {
;           const u16* kp = P + ((size_t)b * SEQ + (size_t)ksub0 * dil + r) * 4608 + 1536 + g * 512 + head * 64;
; #pragma unroll
;           for (int ks = 0; ks < 4; ++ks) kf[ks] = *(const bf16x8*)(kp + ks * 16 + h * 8);
;         } else {
; #pragma unroll
;           for (int ks = 0; ks < 4; ++ks) kf[ks] = zero8();
;         }
;         f32x16 sa = zero16();
; #pragma unroll
;         for (int ks = 0; ks < 4; ++ks) sa = MFMA32(kf[ks], qf[ks], sa);
;         float bm = -INFINITY;
;         const int sbase = c + 128 - 32 * kb - 4 * h;
;         const unsigned slim = (unsigned)((nb * 128 + 32 * wave + c) < 128 ? (nb * 128 + 32 * wave + c) : 128);
;         if (nb > 0 && kb >= 1 && kb <= 3) {
; #pragma unroll
;           for (int i = 0; i < 16; ++i) {
;             const int step = sbase - ((i & 3) + 8 * (i >> 2));
;             const float v = sa[i] + sBias[step];
;             sa[i] = v; bm = fmaxf(bm, v);
;           }
;         } else {
; #pragma unroll
;           for (int i = 0; i < 16; ++i) {
;             const int step = sbase - ((i & 3) + 8 * (i >> 2));
;             const bool valid = (unsigned)step <= slim;
;             const float bv = sBias[step];
;             float v = valid ? sa[i] + bv : -INFINITY;
;             sa[i] = v; bm = fmaxf(bm, v);
;           }
;         }
;         bm = fmaxf(bm, shx(bm, 32));
;         const float mnew = fmaxf(mx, bm);
;         const float mref = (mnew == -INFINITY) ? 0.f : mnew;
;         const float scale = __builtin_amdgcn_exp2f(mx - mref);
;         float ps = 0.f;
; #pragma unroll
;         for (int i = 0; i < 16; ++i) { float pv = __builtin_amdgcn_exp2f(sa[i] - mref); sa[i] = pv; ps += pv; }
;         sum = sum * scale + ps; mx = mnew;
; #pragma unroll
;         for (int i = 0; i < 16; ++i) { oacc[0][i] *= scale; oacc[1][i] *= scale; }
; #pragma unroll
;         for (int s = 0; s < 2; ++s) {
;           bf16x8 pb = pack8(sa, s);
;           const int keybase = 32 * wave + 32 * kb + 16 * s;
; #pragma unroll
;           for (int mb = 0; mb < 2; ++mb) {
;             const u16* vr = Vt + (mb * 32 + c) * 260 + keybase + 4 * h;
.Lattn_end1:
	s_bitcmp1_b32 s2, 2
	s_cbranch_scc1 .Lattn_end2
	ds_read_b128 v[82:85], v217 offset:8192
	ds_read_b128 v[86:89], v218 offset:8192
	ds_read_b128 v[90:93], v219 offset:8192
	ds_read_b128 v[94:97], v220 offset:8192
	ds_read2_b32 v[178:179], v223 offset0:95 offset1:94
	ds_read2_b32 v[180:181], v223 offset0:93 offset1:92
	ds_read2_b32 v[182:183], v223 offset0:87 offset1:86
	ds_read2_b32 v[184:185], v223 offset0:85 offset1:84
	ds_read2_b32 v[186:187], v223 offset0:79 offset1:78
	ds_read2_b32 v[188:189], v223 offset0:77 offset1:76
	ds_read2_b32 v[190:191], v223 offset0:71 offset1:70
	ds_read2_b32 v[192:193], v223 offset0:69 offset1:68
	s_waitcnt lgkmcnt(11)
	v_mfma_f32_32x32x16_bf16 v[130:145], v[82:85], v[66:69], 0
	s_waitcnt lgkmcnt(10)
	v_mfma_f32_32x32x16_bf16 v[130:145], v[86:89], v[70:73], v[130:145]
	s_waitcnt lgkmcnt(9)
	v_mfma_f32_32x32x16_bf16 v[130:145], v[90:93], v[74:77], v[130:145]
	s_waitcnt lgkmcnt(8)
	v_mfma_f32_32x32x16_bf16 v[130:145], v[94:97], v[78:81], v[130:145]
	s_waitcnt lgkmcnt(0)
	s_nop 7
	s_nop 3
	v_add_f32_e32 v130, v130, v178
	v_add_f32_e32 v131, v131, v179
	v_add_f32_e32 v132, v132, v180
	v_add_f32_e32 v133, v133, v181
	v_add_f32_e32 v134, v134, v182
	v_add_f32_e32 v135, v135, v183
	v_add_f32_e32 v136, v136, v184
	v_add_f32_e32 v137, v137, v185
	v_add_f32_e32 v138, v138, v186
	v_add_f32_e32 v139, v139, v187
	v_add_f32_e32 v140, v140, v188
	v_add_f32_e32 v141, v141, v189
	v_add_f32_e32 v142, v142, v190
	v_add_f32_e32 v143, v143, v191
	v_add_f32_e32 v144, v144, v192
	v_add_f32_e32 v145, v145, v193
	ds_read_b64_tr_b16 v[178:179], v221 offset:8192
	ds_read_b64_tr_b16 v[180:181], v221 offset:9216
	ds_read_b64_tr_b16 v[182:183], v222 offset:8192
	ds_read_b64_tr_b16 v[184:185], v222 offset:9216
	ds_read_b64_tr_b16 v[186:187], v221 offset:10240
	ds_read_b64_tr_b16 v[188:189], v221 offset:11264
	ds_read_b64_tr_b16 v[190:191], v222 offset:10240
	ds_read_b64_tr_b16 v[192:193], v222 offset:11264
	v_max3_f32 v235, v130, v131, v132
	v_max3_f32 v235, v235, v133, v134
	v_max3_f32 v235, v235, v135, v136
	v_max3_f32 v235, v235, v137, v138
	v_max3_f32 v235, v235, v139, v140
	v_max3_f32 v235, v235, v141, v142
	v_max3_f32 v235, v235, v143, v144
	v_max_f32_e32 v235, v235, v145
	v_mov_b32_e32 v196, v235
	s_nop 1
	v_permlane32_swap_b32_e32 v196, v235
	v_max_f32_e32 v235, v235, v196
	v_max_f32_e32 v234, v194, v235
	v_cmp_eq_f32_e32 vcc, 0xff800000, v234
	s_nop 1
	v_cndmask_b32_e64 v237, v234, 0, vcc
	v_sub_f32_e32 v196, v194, v237
	v_exp_f32_e32 v233, v196
	v_sub_f32_e32 v130, v130, v237
	v_sub_f32_e32 v131, v131, v237
	v_sub_f32_e32 v132, v132, v237
	v_sub_f32_e32 v133, v133, v237
	v_sub_f32_e32 v134, v134, v237
	v_sub_f32_e32 v135, v135, v237
	v_sub_f32_e32 v136, v136, v237
	v_sub_f32_e32 v137, v137, v237
	v_sub_f32_e32 v138, v138, v237
	v_sub_f32_e32 v139, v139, v237
	v_sub_f32_e32 v140, v140, v237
	v_sub_f32_e32 v141, v141, v237
	v_sub_f32_e32 v142, v142, v237
	v_sub_f32_e32 v143, v143, v237
	v_sub_f32_e32 v144, v144, v237
	v_sub_f32_e32 v145, v145, v237
	v_exp_f32_e32 v130, v130
	v_exp_f32_e32 v131, v131
	v_exp_f32_e32 v132, v132
	v_exp_f32_e32 v133, v133
	v_exp_f32_e32 v134, v134
	v_exp_f32_e32 v135, v135
	v_exp_f32_e32 v136, v136
	v_exp_f32_e32 v137, v137
	v_exp_f32_e32 v138, v138
	v_exp_f32_e32 v139, v139
	v_exp_f32_e32 v140, v140
	v_exp_f32_e32 v141, v141
	v_exp_f32_e32 v142, v142
	v_exp_f32_e32 v143, v143
	v_exp_f32_e32 v144, v144
	v_exp_f32_e32 v145, v145
	v_mov_b32_e32 v194, v234
	v_add_f32_e32 v236, v130, v131
	v_add_f32_e32 v236, v236, v132
	v_add_f32_e32 v236, v236, v133
	v_add_f32_e32 v236, v236, v134
	v_add_f32_e32 v236, v236, v135
	v_add_f32_e32 v236, v236, v136
	v_add_f32_e32 v236, v236, v137
	v_add_f32_e32 v236, v236, v138
	v_add_f32_e32 v236, v236, v139
	v_add_f32_e32 v236, v236, v140
	v_add_f32_e32 v236, v236, v141
	v_add_f32_e32 v236, v236, v142
	v_add_f32_e32 v236, v236, v143
	v_add_f32_e32 v236, v236, v144
	v_add_f32_e32 v236, v236, v145
	v_fma_f32 v195, v195, v233, v236
	v_mul_f32_e32 v146, v233, v146
	v_mul_f32_e32 v147, v233, v147
	v_mul_f32_e32 v148, v233, v148
	v_mul_f32_e32 v149, v233, v149
	v_mul_f32_e32 v150, v233, v150
	v_mul_f32_e32 v151, v233, v151
	v_mul_f32_e32 v152, v233, v152
	v_mul_f32_e32 v153, v233, v153
	v_mul_f32_e32 v154, v233, v154
	v_mul_f32_e32 v155, v233, v155
	v_mul_f32_e32 v156, v233, v156
	v_mul_f32_e32 v157, v233, v157
	v_mul_f32_e32 v158, v233, v158
	v_mul_f32_e32 v159, v233, v159
	v_mul_f32_e32 v160, v233, v160
	v_mul_f32_e32 v161, v233, v161
	v_mul_f32_e32 v162, v233, v162
	v_mul_f32_e32 v163, v233, v163
	v_mul_f32_e32 v164, v233, v164
	v_mul_f32_e32 v165, v233, v165
	v_mul_f32_e32 v166, v233, v166
	v_mul_f32_e32 v167, v233, v167
	v_mul_f32_e32 v168, v233, v168
	v_mul_f32_e32 v169, v233, v169
	v_mul_f32_e32 v170, v233, v170
	v_mul_f32_e32 v171, v233, v171
	v_mul_f32_e32 v172, v233, v172
	v_mul_f32_e32 v173, v233, v173
	v_mul_f32_e32 v174, v233, v174
	v_mul_f32_e32 v175, v233, v175
	v_mul_f32_e32 v176, v233, v176
	v_mul_f32_e32 v177, v233, v177
	v_cvt_pk_bf16_f32 v130, v130, v131
	v_cvt_pk_bf16_f32 v131, v132, v133
	v_cvt_pk_bf16_f32 v132, v134, v135
	v_cvt_pk_bf16_f32 v133, v136, v137
	v_cvt_pk_bf16_f32 v134, v138, v139
	v_cvt_pk_bf16_f32 v135, v140, v141
	v_cvt_pk_bf16_f32 v136, v142, v143
	v_cvt_pk_bf16_f32 v137, v144, v145
	s_waitcnt lgkmcnt(0)
	s_nop 1
	v_mfma_f32_32x32x16_bf16 v[146:161], v[178:181], v[130:133], v[146:161]
	v_mfma_f32_32x32x16_bf16 v[162:177], v[182:185], v[130:133], v[162:177]
	v_mfma_f32_32x32x16_bf16 v[146:161], v[186:189], v[134:137], v[146:161]
	v_mfma_f32_32x32x16_bf16 v[162:177], v[190:193], v[134:137], v[162:177]
; DI void phase_attn_a(int wv_, int vb_, int nvb_, char* ws_, const Ctx& p, char* smem) {
;     ...
;       for (int kb = 0; kb < 5; ++kb) {
;         const int kk = 32 * wave + 32 * kb + c; const int ksub0 = nb * 128 - 128 + kk;
;         bf16x8 kf[4];
;         if (ksub0 >= 0) {
;           const u16* kp = P + ((size_t)b * SEQ + (size_t)ksub0 * dil + r) * 4608 + 1536 + g * 512 + head * 64;
; #pragma unroll
;           for (int ks = 0; ks < 4; ++ks) kf[ks] = *(const bf16x8*)(kp + ks * 16 + h * 8);
;         } else {
; #pragma unroll
;           for (int ks = 0; ks < 4; ++ks) kf[ks] = zero8();
;         }
;         f32x16 sa = zero16();
; #pragma unroll
;         for (int ks = 0; ks < 4; ++ks) sa = MFMA32(kf[ks], qf[ks], sa);
;         float bm = -INFINITY;
;         const int sbase = c + 128 - 32 * kb - 4 * h;
;         const unsigned slim = (unsigned)((nb * 128 + 32 * wave + c) < 128 ? (nb * 128 + 32 * wave + c) : 128);
;         if (nb > 0 && kb >= 1 && kb <= 3) {
; #pragma unroll
;           for (int i = 0; i < 16; ++i) {
;             const int step = sbase - ((i & 3) + 8 * (i >> 2));
;             const float v = sa[i] + sBias[step];
;             sa[i] = v; bm = fmaxf(bm, v);
;           }
;         } else {
; #pragma unroll
;           for (int i = 0; i < 16; ++i) {
;             const int step = sbase - ((i & 3) + 8 * (i >> 2));
;             const bool valid = (unsigned)step <= slim;
;             const float bv = sBias[step];
;             float v = valid ? sa[i] + bv : -INFINITY;
;             sa[i] = v; bm = fmaxf(bm, v);
;           }
;         }
;         bm = fmaxf(bm, shx(bm, 32));
;         const float mnew = fmaxf(mx, bm);
;         const float mref = (mnew == -INFINITY) ? 0.f : mnew;
;         const float scale = __builtin_amdgcn_exp2f(mx - mref);
;         float ps = 0.f;
; #pragma unroll
;         for (int i = 0; i < 16; ++i) { float pv = __builtin_amdgcn_exp2f(sa[i] - mref); sa[i] = pv; ps += pv; }
;         sum = sum * scale + ps; mx = mnew;
; #pragma unroll
;         for (int i = 0; i < 16; ++i) { oacc[0][i] *= scale; oacc[1][i] *= scale; }
; #pragma unroll
;         for (int s = 0; s < 2; ++s) {
;           bf16x8 pb = pack8(sa, s);
;           const int keybase = 32 * wave + 32 * kb + 16 * s;
; #pragma unroll
;           for (int mb = 0; mb < 2; ++mb) {
;             const u16* vr = Vt + (mb * 32 + c) * 260 + keybase + 4 * h;
.Lattn_end2:
	s_bitcmp1_b32 s2, 3
	s_cbranch_scc1 .Lattn_end3
	ds_read_b128 v[82:85], v217 offset:12288
	ds_read_b128 v[86:89], v218 offset:12288
	ds_read_b128 v[90:93], v219 offset:12288
	ds_read_b128 v[94:97], v220 offset:12288
	ds_read2_b32 v[178:179], v223 offset0:63 offset1:62
	ds_read2_b32 v[180:181], v223 offset0:61 offset1:60
	ds_read2_b32 v[182:183], v223 offset0:55 offset1:54
	ds_read2_b32 v[184:185], v223 offset0:53 offset1:52
	ds_read2_b32 v[186:187], v223 offset0:47 offset1:46
	ds_read2_b32 v[188:189], v223 offset0:45 offset1:44
	ds_read2_b32 v[190:191], v223 offset0:39 offset1:38
	ds_read2_b32 v[192:193], v223 offset0:37 offset1:36
	s_waitcnt lgkmcnt(11)
	v_mfma_f32_32x32x16_bf16 v[130:145], v[82:85], v[66:69], 0
	s_waitcnt lgkmcnt(10)
	v_mfma_f32_32x32x16_bf16 v[130:145], v[86:89], v[70:73], v[130:145]
	s_waitcnt lgkmcnt(9)
	v_mfma_f32_32x32x16_bf16 v[130:145], v[90:93], v[74:77], v[130:145]
	s_waitcnt lgkmcnt(8)
	v_mfma_f32_32x32x16_bf16 v[130:145], v[94:97], v[78:81], v[130:145]
	s_waitcnt lgkmcnt(0)
	s_nop 7
	s_nop 3
	v_add_f32_e32 v130, v130, v178
	v_add_f32_e32 v131, v131, v179
	v_add_f32_e32 v132, v132, v180
	v_add_f32_e32 v133, v133, v181
	v_add_f32_e32 v134, v134, v182
	v_add_f32_e32 v135, v135, v183
	v_add_f32_e32 v136, v136, v184
	v_add_f32_e32 v137, v137, v185
	v_add_f32_e32 v138, v138, v186
	v_add_f32_e32 v139, v139, v187
	v_add_f32_e32 v140, v140, v188
	v_add_f32_e32 v141, v141, v189
	v_add_f32_e32 v142, v142, v190
	v_add_f32_e32 v143, v143, v191
	v_add_f32_e32 v144, v144, v192
	v_add_f32_e32 v145, v145, v193
	ds_read_b64_tr_b16 v[178:179], v221 offset:12288
	ds_read_b64_tr_b16 v[180:181], v221 offset:13312
	ds_read_b64_tr_b16 v[182:183], v222 offset:12288
	ds_read_b64_tr_b16 v[184:185], v222 offset:13312
	ds_read_b64_tr_b16 v[186:187], v221 offset:14336
	ds_read_b64_tr_b16 v[188:189], v221 offset:15360
	ds_read_b64_tr_b16 v[190:191], v222 offset:14336
	ds_read_b64_tr_b16 v[192:193], v222 offset:15360
	v_max3_f32 v235, v130, v131, v132
	v_max3_f32 v235, v235, v133, v134
	v_max3_f32 v235, v235, v135, v136
	v_max3_f32 v235, v235, v137, v138
	v_max3_f32 v235, v235, v139, v140
	v_max3_f32 v235, v235, v141, v142
	v_max3_f32 v235, v235, v143, v144
	v_max_f32_e32 v235, v235, v145
	v_mov_b32_e32 v196, v235
	s_nop 1
	v_permlane32_swap_b32_e32 v196, v235
	v_max_f32_e32 v235, v235, v196
	v_max_f32_e32 v234, v194, v235
	v_cmp_eq_f32_e32 vcc, 0xff800000, v234
	s_nop 1
	v_cndmask_b32_e64 v237, v234, 0, vcc
	v_sub_f32_e32 v196, v194, v237
	v_exp_f32_e32 v233, v196
	v_sub_f32_e32 v130, v130, v237
	v_sub_f32_e32 v131, v131, v237
	v_sub_f32_e32 v132, v132, v237
	v_sub_f32_e32 v133, v133, v237
	v_sub_f32_e32 v134, v134, v237
	v_sub_f32_e32 v135, v135, v237
	v_sub_f32_e32 v136, v136, v237
	v_sub_f32_e32 v137, v137, v237
	v_sub_f32_e32 v138, v138, v237
	v_sub_f32_e32 v139, v139, v237
	v_sub_f32_e32 v140, v140, v237
	v_sub_f32_e32 v141, v141, v237
	v_sub_f32_e32 v142, v142, v237
	v_sub_f32_e32 v143, v143, v237
	v_sub_f32_e32 v144, v144, v237
	v_sub_f32_e32 v145, v145, v237
	v_exp_f32_e32 v130, v130
	v_exp_f32_e32 v131, v131
	v_exp_f32_e32 v132, v132
	v_exp_f32_e32 v133, v133
	v_exp_f32_e32 v134, v134
	v_exp_f32_e32 v135, v135
	v_exp_f32_e32 v136, v136
	v_exp_f32_e32 v137, v137
	v_exp_f32_e32 v138, v138
	v_exp_f32_e32 v139, v139
	v_exp_f32_e32 v140, v140
	v_exp_f32_e32 v141, v141
	v_exp_f32_e32 v142, v142
	v_exp_f32_e32 v143, v143
	v_exp_f32_e32 v144, v144
	v_exp_f32_e32 v145, v145
	v_mov_b32_e32 v194, v234
	v_add_f32_e32 v236, v130, v131
	v_add_f32_e32 v236, v236, v132
	v_add_f32_e32 v236, v236, v133
	v_add_f32_e32 v236, v236, v134
	v_add_f32_e32 v236, v236, v135
	v_add_f32_e32 v236, v236, v136
	v_add_f32_e32 v236, v236, v137
	v_add_f32_e32 v236, v236, v138
	v_add_f32_e32 v236, v236, v139
	v_add_f32_e32 v236, v236, v140
	v_add_f32_e32 v236, v236, v141
	v_add_f32_e32 v236, v236, v142
	v_add_f32_e32 v236, v236, v143
	v_add_f32_e32 v236, v236, v144
	v_add_f32_e32 v236, v236, v145
	v_fma_f32 v195, v195, v233, v236
	v_mul_f32_e32 v146, v233, v146
	v_mul_f32_e32 v147, v233, v147
	v_mul_f32_e32 v148, v233, v148
	v_mul_f32_e32 v149, v233, v149
	v_mul_f32_e32 v150, v233, v150
	v_mul_f32_e32 v151, v233, v151
	v_mul_f32_e32 v152, v233, v152
	v_mul_f32_e32 v153, v233, v153
	v_mul_f32_e32 v154, v233, v154
	v_mul_f32_e32 v155, v233, v155
	v_mul_f32_e32 v156, v233, v156
	v_mul_f32_e32 v157, v233, v157
	v_mul_f32_e32 v158, v233, v158
	v_mul_f32_e32 v159, v233, v159
	v_mul_f32_e32 v160, v233, v160
	v_mul_f32_e32 v161, v233, v161
	v_mul_f32_e32 v162, v233, v162
	v_mul_f32_e32 v163, v233, v163
	v_mul_f32_e32 v164, v233, v164
	v_mul_f32_e32 v165, v233, v165
	v_mul_f32_e32 v166, v233, v166
	v_mul_f32_e32 v167, v233, v167
	v_mul_f32_e32 v168, v233, v168
	v_mul_f32_e32 v169, v233, v169
	v_mul_f32_e32 v170, v233, v170
	v_mul_f32_e32 v171, v233, v171
	v_mul_f32_e32 v172, v233, v172
	v_mul_f32_e32 v173, v233, v173
	v_mul_f32_e32 v174, v233, v174
	v_mul_f32_e32 v175, v233, v175
	v_mul_f32_e32 v176, v233, v176
	v_mul_f32_e32 v177, v233, v177
	v_cvt_pk_bf16_f32 v130, v130, v131
	v_cvt_pk_bf16_f32 v131, v132, v133
	v_cvt_pk_bf16_f32 v132, v134, v135
	v_cvt_pk_bf16_f32 v133, v136, v137
	v_cvt_pk_bf16_f32 v134, v138, v139
	v_cvt_pk_bf16_f32 v135, v140, v141
	v_cvt_pk_bf16_f32 v136, v142, v143
	v_cvt_pk_bf16_f32 v137, v144, v145
	s_waitcnt lgkmcnt(0)
	s_nop 1
	v_mfma_f32_32x32x16_bf16 v[146:161], v[178:181], v[130:133], v[146:161]
	v_mfma_f32_32x32x16_bf16 v[162:177], v[182:185], v[130:133], v[162:177]
	v_mfma_f32_32x32x16_bf16 v[146:161], v[186:189], v[134:137], v[146:161]
	v_mfma_f32_32x32x16_bf16 v[162:177], v[190:193], v[134:137], v[162:177]
; DI void phase_attn_a(int wv_, int vb_, int nvb_, char* ws_, const Ctx& p, char* smem) {
;     ...
;       for (int kb = 0; kb < 5; ++kb) {
;         const int kk = 32 * wave + 32 * kb + c; const int ksub0 = nb * 128 - 128 + kk;
;         bf16x8 kf[4];
;         if (ksub0 >= 0) {
;           const u16* kp = P + ((size_t)b * SEQ + (size_t)ksub0 * dil + r) * 4608 + 1536 + g * 512 + head * 64;
; #pragma unroll
;           for (int ks = 0; ks < 4; ++ks) kf[ks] = *(const bf16x8*)(kp + ks * 16 + h * 8);
;         } else {
; #pragma unroll
;           for (int ks = 0; ks < 4; ++ks) kf[ks] = zero8();
;         }
;         f32x16 sa = zero16();
; #pragma unroll
;         for (int ks = 0; ks < 4; ++ks) sa = MFMA32(kf[ks], qf[ks], sa);
;         float bm = -INFINITY;
;         const int sbase = c + 128 - 32 * kb - 4 * h;
;         const unsigned slim = (unsigned)((nb * 128 + 32 * wave + c) < 128 ? (nb * 128 + 32 * wave + c) : 128);
;         if (nb > 0 && kb >= 1 && kb <= 3) {
; #pragma unroll
;           for (int i = 0; i < 16; ++i) {
;             const int step = sbase - ((i & 3) + 8 * (i >> 2));
;             const float v = sa[i] + sBias[step];
;             sa[i] = v; bm = fmaxf(bm, v);
;           }
;         } else {
; #pragma unroll
;           for (int i = 0; i < 16; ++i) {
;             const int step = sbase - ((i & 3) + 8 * (i >> 2));
;             const bool valid = (unsigned)step <= slim;
;             const float bv = sBias[step];
;             float v = valid ? sa[i] + bv : -INFINITY;
;             sa[i] = v; bm = fmaxf(bm, v);
;           }
;         }
;         bm = fmaxf(bm, shx(bm, 32));
;         const float mnew = fmaxf(mx, bm);
;         const float mref = (mnew == -INFINITY) ? 0.f : mnew;
;         const float scale = __builtin_amdgcn_exp2f(mx - mref);
;         float ps = 0.f;
; #pragma unroll
;         for (int i = 0; i < 16; ++i) { float pv = __builtin_amdgcn_exp2f(sa[i] - mref); sa[i] = pv; ps += pv; }
;         sum = sum * scale + ps; mx = mnew;
; #pragma unroll
;         for (int i = 0; i < 16; ++i) { oacc[0][i] *= scale; oacc[1][i] *= scale; }
; #pragma unroll
;         for (int s = 0; s < 2; ++s) {
;           bf16x8 pb = pack8(sa, s);
;           const int keybase = 32 * wave + 32 * kb + 16 * s;
; #pragma unroll
;           for (int mb = 0; mb < 2; ++mb) {
;             const u16* vr = Vt + (mb * 32 + c) * 260 + keybase + 4 * h;
.Lattn_end3:
	s_bitcmp1_b32 s2, 4
	s_cbranch_scc1 .Lattn_skip4
	ds_read_b128 v[82:85], v217 offset:16384
	ds_read_b128 v[86:89], v218 offset:16384
	ds_read_b128 v[90:93], v219 offset:16384
	ds_read_b128 v[94:97], v220 offset:16384
	ds_read2_b32 v[178:179], v223 offset0:31 offset1:30
	ds_read2_b32 v[180:181], v223 offset0:29 offset1:28
	ds_read2_b32 v[182:183], v223 offset0:23 offset1:22
	ds_read2_b32 v[184:185], v223 offset0:21 offset1:20
	ds_read2_b32 v[186:187], v223 offset0:15 offset1:14
	ds_read2_b32 v[188:189], v223 offset0:13 offset1:12
	ds_read2_b32 v[190:191], v223 offset0:7 offset1:6
	ds_read2_b32 v[192:193], v223 offset0:5 offset1:4
	s_waitcnt lgkmcnt(11)
	v_mfma_f32_32x32x16_bf16 v[130:145], v[82:85], v[66:69], 0
	s_waitcnt lgkmcnt(10)
	v_mfma_f32_32x32x16_bf16 v[130:145], v[86:89], v[70:73], v[130:145]
	s_waitcnt lgkmcnt(9)
	v_mfma_f32_32x32x16_bf16 v[130:145], v[90:93], v[74:77], v[130:145]
	s_waitcnt lgkmcnt(8)
	v_mfma_f32_32x32x16_bf16 v[130:145], v[94:97], v[78:81], v[130:145]
	global_load_dwordx4 v[66:69], v232, s[8:9]
	global_load_dwordx4 v[70:73], v232, s[8:9] offset:32
	global_load_dwordx4 v[74:77], v232, s[8:9] offset:64
	global_load_dwordx4 v[78:81], v232, s[8:9] offset:96
	s_waitcnt lgkmcnt(0)
	s_nop 7
	s_nop 3
	v_add_f32_e32 v130, v130, v178
	v_add_f32_e32 v131, v131, v179
	v_add_f32_e32 v132, v132, v180
	v_add_f32_e32 v133, v133, v181
	v_add_f32_e32 v134, v134, v182
	v_add_f32_e32 v135, v135, v183
	v_add_f32_e32 v136, v136, v184
	v_add_f32_e32 v137, v137, v185
	v_add_f32_e32 v138, v138, v186
	v_add_f32_e32 v139, v139, v187
	v_add_f32_e32 v140, v140, v188
	v_add_f32_e32 v141, v141, v189
	v_add_f32_e32 v142, v142, v190
	v_add_f32_e32 v143, v143, v191
	v_add_f32_e32 v144, v144, v192
	v_add_f32_e32 v145, v145, v193
	ds_read_b64_tr_b16 v[178:179], v221 offset:16384
	ds_read_b64_tr_b16 v[180:181], v221 offset:17408
	ds_read_b64_tr_b16 v[182:183], v222 offset:16384
	ds_read_b64_tr_b16 v[184:185], v222 offset:17408
	ds_read_b64_tr_b16 v[186:187], v221 offset:18432
	ds_read_b64_tr_b16 v[188:189], v221 offset:19456
	ds_read_b64_tr_b16 v[190:191], v222 offset:18432
	ds_read_b64_tr_b16 v[192:193], v222 offset:19456
	v_max3_f32 v235, v130, v131, v132
	v_max3_f32 v235, v235, v133, v134
	v_max3_f32 v235, v235, v135, v136
	v_max3_f32 v235, v235, v137, v138
	v_max3_f32 v235, v235, v139, v140
	v_max3_f32 v235, v235, v141, v142
	v_max3_f32 v235, v235, v143, v144
	v_max_f32_e32 v235, v235, v145
	v_mov_b32_e32 v196, v235
	s_nop 1
	v_permlane32_swap_b32_e32 v196, v235
	v_max_f32_e32 v235, v235, v196
	v_max_f32_e32 v234, v194, v235
	v_cmp_eq_f32_e32 vcc, 0xff800000, v234
	s_nop 1
	v_cndmask_b32_e64 v237, v234, 0, vcc
	v_sub_f32_e32 v196, v194, v237
	v_exp_f32_e32 v233, v196
	v_sub_f32_e32 v130, v130, v237
	v_sub_f32_e32 v131, v131, v237
	v_sub_f32_e32 v132, v132, v237
	v_sub_f32_e32 v133, v133, v237
	v_sub_f32_e32 v134, v134, v237
	v_sub_f32_e32 v135, v135, v237
	v_sub_f32_e32 v136, v136, v237
	v_sub_f32_e32 v137, v137, v237
	v_sub_f32_e32 v138, v138, v237
	v_sub_f32_e32 v139, v139, v237
	v_sub_f32_e32 v140, v140, v237
	v_sub_f32_e32 v141, v141, v237
	v_sub_f32_e32 v142, v142, v237
	v_sub_f32_e32 v143, v143, v237
	v_sub_f32_e32 v144, v144, v237
	v_sub_f32_e32 v145, v145, v237
	v_exp_f32_e32 v130, v130
	v_exp_f32_e32 v131, v131
	v_exp_f32_e32 v132, v132
	v_exp_f32_e32 v133, v133
	v_exp_f32_e32 v134, v134
	v_exp_f32_e32 v135, v135
	v_exp_f32_e32 v136, v136
	v_exp_f32_e32 v137, v137
	v_exp_f32_e32 v138, v138
	v_exp_f32_e32 v139, v139
	v_exp_f32_e32 v140, v140
	v_exp_f32_e32 v141, v141
	v_exp_f32_e32 v142, v142
	v_exp_f32_e32 v143, v143
	v_exp_f32_e32 v144, v144
	v_exp_f32_e32 v145, v145
	v_mov_b32_e32 v194, v234
	v_add_f32_e32 v236, v130, v131
	v_add_f32_e32 v236, v236, v132
	v_add_f32_e32 v236, v236, v133
	v_add_f32_e32 v236, v236, v134
	v_add_f32_e32 v236, v236, v135
	v_add_f32_e32 v236, v236, v136
	v_add_f32_e32 v236, v236, v137
	v_add_f32_e32 v236, v236, v138
	v_add_f32_e32 v236, v236, v139
	v_add_f32_e32 v236, v236, v140
	v_add_f32_e32 v236, v236, v141
	v_add_f32_e32 v236, v236, v142
	v_add_f32_e32 v236, v236, v143
	v_add_f32_e32 v236, v236, v144
	v_add_f32_e32 v236, v236, v145
	v_fma_f32 v195, v195, v233, v236
	v_mul_f32_e32 v146, v233, v146
	v_mul_f32_e32 v147, v233, v147
	v_mul_f32_e32 v148, v233, v148
	v_mul_f32_e32 v149, v233, v149
	v_mul_f32_e32 v150, v233, v150
	v_mul_f32_e32 v151, v233, v151
	v_mul_f32_e32 v152, v233, v152
	v_mul_f32_e32 v153, v233, v153
	v_mul_f32_e32 v154, v233, v154
	v_mul_f32_e32 v155, v233, v155
	v_mul_f32_e32 v156, v233, v156
	v_mul_f32_e32 v157, v233, v157
	v_mul_f32_e32 v158, v233, v158
	v_mul_f32_e32 v159, v233, v159
	v_mul_f32_e32 v160, v233, v160
	v_mul_f32_e32 v161, v233, v161
	v_mul_f32_e32 v162, v233, v162
	v_mul_f32_e32 v163, v233, v163
	v_mul_f32_e32 v164, v233, v164
	v_mul_f32_e32 v165, v233, v165
	v_mul_f32_e32 v166, v233, v166
	v_mul_f32_e32 v167, v233, v167
	v_mul_f32_e32 v168, v233, v168
	v_mul_f32_e32 v169, v233, v169
	v_mul_f32_e32 v170, v233, v170
	v_mul_f32_e32 v171, v233, v171
	v_mul_f32_e32 v172, v233, v172
	v_mul_f32_e32 v173, v233, v173
	v_mul_f32_e32 v174, v233, v174
	v_mul_f32_e32 v175, v233, v175
	v_mul_f32_e32 v176, v233, v176
	v_mul_f32_e32 v177, v233, v177
	v_cvt_pk_bf16_f32 v130, v130, v131
	v_cvt_pk_bf16_f32 v131, v132, v133
	v_cvt_pk_bf16_f32 v132, v134, v135
	v_cvt_pk_bf16_f32 v133, v136, v137
	v_cvt_pk_bf16_f32 v134, v138, v139
	v_cvt_pk_bf16_f32 v135, v140, v141
	v_cvt_pk_bf16_f32 v136, v142, v143
	v_cvt_pk_bf16_f32 v137, v144, v145
	s_waitcnt lgkmcnt(0)
	s_nop 1
	v_mfma_f32_32x32x16_bf16 v[146:161], v[178:181], v[130:133], v[146:161]
	v_mfma_f32_32x32x16_bf16 v[162:177], v[182:185], v[130:133], v[162:177]
	v_mfma_f32_32x32x16_bf16 v[146:161], v[186:189], v[134:137], v[146:161]
	v_mfma_f32_32x32x16_bf16 v[162:177], v[190:193], v[134:137], v[162:177]
	s_branch .Lattn_end4
; DI float shx(float v, int m) { return __int_as_float(__builtin_amdgcn_ds_bpermute((lane_now() ^ m) << 2, __float_as_int(v))); }
; DI int shx(int v, int m) { return __builtin_amdgcn_ds_bpermute((lane_now() ^ m) << 2, v); }
; DI u16 f2bf(float x) { return (u16)(pk2bf(x, 0.f) & 0xffffu); }
; DI void phase_attn_a(int wv_, int vb_, int nvb_, char* ws_, const Ctx& p, char* smem) {
;     ...
;       sum += shx(sum, 32);
;       const float inv = 1.0f / sum;
;       u16* op = Og + ((size_t)b * SEQ + qtok) * 512 + head * 64;
; #pragma unroll
;       for (int mb = 0; mb < 2; ++mb)
; #pragma unroll
;         for (int ig = 0; ig < 4; ++ig) {
;           s16x4 o;
; #pragma unroll
;           for (int q = 0; q < 4; ++q) o[q] = (short)f2bf(oacc[mb][ig * 4 + q] * inv);
;           *(s16x4*)(op + mb * 32 + 8 * ig + 4 * h) = o;
;         }
;       if (h == 0) lse[((size_t)b * SEQ + qtok) * 8 + head] = (mx + log2f(sum)) * 0.6931471805599453f;
;     }
;     __syncthreads();
.Lattn_skip4:
	global_load_dwordx4 v[66:69], v232, s[8:9]
	global_load_dwordx4 v[70:73], v232, s[8:9] offset:32
	global_load_dwordx4 v[74:77], v232, s[8:9] offset:64
	global_load_dwordx4 v[78:81], v232, s[8:9] offset:96
.Lattn_end4:
	s_nop 7
	s_nop 7
	v_mov_b32_e32 v196, v195
	s_nop 1
	v_permlane32_swap_b32_e32 v196, v195
	v_add_f32_e32 v195, v195, v196
	v_rcp_f32_e32 v238, v195
	v_log_f32_e32 v197, v195
	s_nop 0
	v_mul_f32_e32 v146, v238, v146
	v_mul_f32_e32 v147, v238, v147
	v_mul_f32_e32 v148, v238, v148
	v_mul_f32_e32 v149, v238, v149
	v_mul_f32_e32 v150, v238, v150
	v_mul_f32_e32 v151, v238, v151
	v_mul_f32_e32 v152, v238, v152
	v_mul_f32_e32 v153, v238, v153
	v_mul_f32_e32 v154, v238, v154
	v_mul_f32_e32 v155, v238, v155
	v_mul_f32_e32 v156, v238, v156
	v_mul_f32_e32 v157, v238, v157
	v_mul_f32_e32 v158, v238, v158
	v_mul_f32_e32 v159, v238, v159
	v_mul_f32_e32 v160, v238, v160
	v_mul_f32_e32 v161, v238, v161
	v_mul_f32_e32 v162, v238, v162
	v_mul_f32_e32 v163, v238, v163
	v_mul_f32_e32 v164, v238, v164
	v_mul_f32_e32 v165, v238, v165
	v_mul_f32_e32 v166, v238, v166
	v_mul_f32_e32 v167, v238, v167
	v_mul_f32_e32 v168, v238, v168
	v_mul_f32_e32 v169, v238, v169
	v_mul_f32_e32 v170, v238, v170
	v_mul_f32_e32 v171, v238, v171
	v_mul_f32_e32 v172, v238, v172
	v_mul_f32_e32 v173, v238, v173
	v_mul_f32_e32 v174, v238, v174
	v_mul_f32_e32 v175, v238, v175
	v_mul_f32_e32 v176, v238, v176
	v_mul_f32_e32 v177, v238, v177
	v_cvt_pk_bf16_f32 v146, v146, v147
	v_cvt_pk_bf16_f32 v147, v148, v149
	v_cvt_pk_bf16_f32 v150, v150, v151
	v_cvt_pk_bf16_f32 v151, v152, v153
	v_cvt_pk_bf16_f32 v154, v154, v155
	v_cvt_pk_bf16_f32 v155, v156, v157
	v_cvt_pk_bf16_f32 v158, v158, v159
	v_cvt_pk_bf16_f32 v159, v160, v161
	v_cvt_pk_bf16_f32 v162, v162, v163
	v_cvt_pk_bf16_f32 v163, v164, v165
	v_cvt_pk_bf16_f32 v166, v166, v167
	v_cvt_pk_bf16_f32 v167, v168, v169
	v_cvt_pk_bf16_f32 v170, v170, v171
	v_cvt_pk_bf16_f32 v171, v172, v173
	v_cvt_pk_bf16_f32 v174, v174, v175
	v_cvt_pk_bf16_f32 v175, v176, v177
	global_store_dwordx2 v225, v[146:147], s[4:5]
	global_store_dwordx2 v225, v[150:151], s[4:5] offset:16
	global_store_dwordx2 v225, v[154:155], s[4:5] offset:32
	global_store_dwordx2 v225, v[158:159], s[4:5] offset:48
	global_store_dwordx2 v225, v[162:163], s[4:5] offset:64
	global_store_dwordx2 v225, v[166:167], s[4:5] offset:80
	global_store_dwordx2 v225, v[170:171], s[4:5] offset:96
	global_store_dwordx2 v225, v[174:175], s[4:5] offset:112
	v_add_f32_e32 v197, v194, v197
	v_mul_f32_e32 v197, 0x3f317218, v197
	s_mov_b32 exec_hi, 0
	global_store_dword v227, v197, s[6:7]
	s_mov_b32 exec_hi, -1
	s_add_i32 s34, s34, 1
	s_cmp_lt_i32 s34, s35
	s_cbranch_scc1 .Lattn_loop
	s_waitcnt vmcnt(0)
	s_barrier
